# v45: P2/P8 residual epilogues use per-row-group counted vmcnt waits instead of one vmcnt(0) after the 16 residual loads
# baseline (speedup 1.0000x reference)
; __device__ __forceinline__ u32x4 pack8(const f32x4 a, const f32x4 b) { u32x4 w; w.x = cvtpk(a[0], a[1]); w.y = cvtpk(a[2], a[3]); w.z = cvtpk(b[0], b[1]); w.w = cvtpk(b[2], b[3]); return w; }
; __device__ __forceinline__ void unpack8(const u32x4 w, f32x4& a, f32x4& b) { a = (f32x4){bflo(w.x), bfhi(w.x), bflo(w.y), bfhi(w.y)}; b = (f32x4){bflo(w.z), bfhi(w.z), bflo(w.w), bfhi(w.w)}; }
;     __device__ __forceinline__ void operator()(const Acc& acc, const Unit& u, int wr, int wc, int fr, int fq) const {
;         const size_t off0 = (size_t)(u.pm * BM + wr * 64 + fr) * D + u.pn * BM + wc * 32 + 8 * fq;
;         u32x4 bw[2][4][2];
; #pragma unroll
;         for (int ai = 0; ai < 2; ++ai)
; #pragma unroll
;             for (int m = 0; m < 4; ++m)
; #pragma unroll
;                 for (int bj = 0; bj < 2; ++bj) bw[ai][m][bj] = *(const u32x4*)((const bf16_t*)base + off0 + (size_t)(ai * HALF + m * 16) * D + bj * HALF);
; #pragma unroll
;         for (int ai = 0; ai < 2; ++ai)
; #pragma unroll
;             for (int m = 0; m < 4; ++m) {
;                 const int row = u.pm * BM + ai * HALF + wr * 64 + m * 16 + fr; float s = 0.f;
; #pragma unroll
;                 for (int bj = 0; bj < 2; ++bj) {
;                     const size_t off = off0 + (size_t)(ai * HALF + m * 16) * D + bj * HALF;
;                     f32x4 b0, b1; unpack8(bw[ai][m][bj], b0, b1);
;                     const f32x4 v0 = b0 + acc[ai][bj][m][0] * scale, v1 = b1 + acc[ai][bj][m][1] * scale;
;                     s += (v0[0] * v0[0] + v0[1] * v0[1]) + (v0[2] * v0[2] + v0[3] * v0[3]) + (v1[0] * v1[0] + v1[1] * v1[1]) + (v1[2] * v1[2] + v1[3] * v1[3]);
;                     if (OUT_F32) { *(f32x4*)(outf + off) = v0; *(f32x4*)(outf + off + 4) = v1; }
;                     if (OUT_BF16) *(u32x4*)(outb + off) = pack8(v0, v1);
;                 }
;                 s += __shfl_xor(s, 16); s += __shfl_xor(s, 32);
;                 if (fq == 0) ssq[(size_t)row * 16 + u.pn * 4 + wc] = s;
;             }
.LBB0_681:
	v_lshl_add_u32 v206, s84, 8, v212
	v_ashrrev_i32_e32 v207, 31, v206
	v_readlane_b32 s88, v252, 16
	s_lshl_b32 s38, s18, 8
	v_lshlrev_b64 v[118:119], 11, v[206:207]
	v_readlane_b32 s89, v252, 17
	s_ashr_i32 s39, s38, 31
	v_and_b32_e32 v219, 64, v217
	v_lshl_add_u64 v[118:119], s[88:89], 0, v[118:119]
	v_lshl_add_u64 v[118:119], s[38:39], 1, v[118:119]
	v_lshl_add_u64 v[208:209], v[118:119], 0, v[194:195]
	global_load_dwordx4 v[220:223], v[208:209], off
	global_load_dwordx4 v[224:227], v[208:209], off offset:256
	v_add_co_u32_e32 v118, vcc, 0x8000, v208
	s_mov_b32 s38, 0x10000
	s_nop 0
	v_addc_co_u32_e32 v119, vcc, 0, v209, vcc
	v_add_co_u32_e32 v120, vcc, s38, v208
	s_mov_b32 s38, 0x18000
	s_nop 0
	v_addc_co_u32_e32 v121, vcc, 0, v209, vcc
	global_load_dwordx4 v[182:185], v[118:119], off
	global_load_dwordx4 v[178:181], v[118:119], off offset:256
	v_add_co_u32_e32 v118, vcc, s38, v208
	s_mov_b32 s38, 0x40000
	s_nop 0
	v_addc_co_u32_e32 v119, vcc, 0, v209, vcc
	global_load_dwordx4 v[174:177], v[120:121], off
	global_load_dwordx4 v[170:173], v[120:121], off offset:256
	v_add_co_u32_e32 v120, vcc, s38, v208
	s_mov_b32 s38, 0x48000
	s_nop 0
	v_addc_co_u32_e32 v121, vcc, 0, v209, vcc
	global_load_dwordx4 v[166:169], v[118:119], off
	global_load_dwordx4 v[162:165], v[118:119], off offset:256
	v_add_co_u32_e32 v118, vcc, s38, v208
	s_mov_b32 s38, 0x50000
	s_nop 0
	v_addc_co_u32_e32 v119, vcc, 0, v209, vcc
	global_load_dwordx4 v[158:161], v[120:121], off
	global_load_dwordx4 v[154:157], v[120:121], off offset:256
	v_add_co_u32_e32 v120, vcc, s38, v208
	s_mov_b32 s38, 0x58000
	s_nop 0
	v_addc_co_u32_e32 v121, vcc, 0, v209, vcc
	global_load_dwordx4 v[150:153], v[118:119], off
	global_load_dwordx4 v[146:149], v[118:119], off offset:256
	v_add_co_u32_e32 v118, vcc, s38, v208
	global_load_dwordx4 v[142:145], v[120:121], off
	global_load_dwordx4 v[138:141], v[120:121], off offset:256
	v_addc_co_u32_e32 v119, vcc, 0, v209, vcc
	global_load_dwordx4 v[126:129], v[118:119], off
	s_nop 0
	global_load_dwordx4 v[118:121], v[118:119], off offset:256
	v_xor_b32_e32 v218, 16, v217
	v_add_u32_e32 v219, 64, v219
	v_xor_b32_e32 v228, 32, v217
	v_cmp_lt_i32_e32 vcc, v218, v219
	s_lshl_b32 s38, s18, 2
	s_ashr_i32 s39, s38, 31
	v_cndmask_b32_e32 v218, v217, v218, vcc
	v_cmp_lt_i32_e32 vcc, v228, v219
	v_lshlrev_b32_e32 v219, 2, v218
	s_waitcnt vmcnt(14)
	v_and_b32_e32 v229, 0xffff0000, v220
	v_cndmask_b32_e32 v228, v217, v228, vcc
	v_lshlrev_b32_e32 v218, 2, v228
	v_lshlrev_b32_e32 v228, 16, v220
	v_lshlrev_b32_e32 v220, 16, v221
	v_and_b32_e32 v221, 0xffff0000, v221
	v_lshlrev_b32_e32 v230, 16, v222
	v_and_b32_e32 v231, 0xffff0000, v222
	v_lshlrev_b32_e32 v222, 16, v223
	v_and_b32_e32 v223, 0xffff0000, v223
	v_pk_fma_f32 v[136:137], v[136:137], 0.5, v[220:221] op_sel_hi:[1,0,1]
	v_pk_fma_f32 v[134:135], v[134:135], 0.5, v[228:229] op_sel_hi:[1,0,1]
	v_pk_fma_f32 v[220:221], v[132:133], 0.5, v[222:223] op_sel_hi:[1,0,1]
	v_pk_fma_f32 v[132:133], v[130:131], 0.5, v[230:231] op_sel_hi:[1,0,1]
	v_mul_f32_e32 v130, v135, v135
	v_mul_f32_e32 v131, v137, v137
	v_mul_f32_e32 v222, v133, v133
	v_fmac_f32_e32 v130, v134, v134
	v_fmac_f32_e32 v131, v136, v136
	v_mul_f32_e32 v223, v221, v221
	v_fmac_f32_e32 v222, v132, v132
	v_add_f32_e32 v130, v130, v131
	v_add_f32_e32 v130, v222, v130
	v_fmac_f32_e32 v223, v220, v220
	v_add_f32_e32 v228, v223, v130
	v_cvt_pk_bf16_f32 v130, v134, v135
	v_cvt_pk_bf16_f32 v131, v136, v137
	v_lshlrev_b32_e32 v134, 16, v224
	v_and_b32_e32 v135, 0xffff0000, v224
	v_lshlrev_b32_e32 v136, 16, v225
	v_and_b32_e32 v137, 0xffff0000, v225
	v_lshlrev_b32_e32 v222, 16, v226
	v_and_b32_e32 v223, 0xffff0000, v226
	v_pk_fma_f32 v[124:125], v[124:125], 0.5, v[136:137] op_sel_hi:[1,0,1]
	v_pk_fma_f32 v[122:123], v[122:123], 0.5, v[134:135] op_sel_hi:[1,0,1]
	v_pk_fma_f32 v[134:135], v[114:115], 0.5, v[222:223] op_sel_hi:[1,0,1]
	v_mul_f32_e32 v114, v123, v123
	v_mul_f32_e32 v115, v125, v125
	v_fmac_f32_e32 v114, v122, v122
	v_fmac_f32_e32 v115, v124, v124
	v_lshlrev_b32_e32 v224, 16, v227
	v_and_b32_e32 v225, 0xffff0000, v227
	v_add_f32_e32 v114, v114, v115
	v_mul_f32_e32 v115, v135, v135
	v_pk_fma_f32 v[116:117], v[116:117], 0.5, v[224:225] op_sel_hi:[1,0,1]
	v_fmac_f32_e32 v115, v134, v134
	v_add_f32_e32 v114, v115, v114
	v_mul_f32_e32 v115, v117, v117
	v_fmac_f32_e32 v115, v116, v116
	v_add_f32_e32 v114, v115, v114
	v_add_f32_e32 v114, v228, v114
	v_mov_b32_e32 v115, v114
	s_nop 1
	v_permlane16_swap_b32_e32 v114, v115
	v_cvt_pk_bf16_f32 v132, v132, v133
	v_cvt_pk_bf16_f32 v133, v220, v221
	v_cvt_pk_bf16_f32 v122, v122, v123
	v_cvt_pk_bf16_f32 v123, v124, v125
	s_waitcnt lgkmcnt(0)
	v_add_f32_e32 v114, v114, v115
	v_mov_b32_e32 v115, v114
	s_nop 1
	v_permlane32_swap_b32_e32 v114, v115
	v_cvt_pk_bf16_f32 v124, v134, v135
	v_cvt_pk_bf16_f32 v125, v116, v117
	global_store_dwordx4 v[208:209], v[130:133], off
	global_store_dwordx4 v[208:209], v[122:125], off offset:256
	s_and_saveexec_b64 s[40:41], s[4:5]
	s_cbranch_execz .LBB0_683
	v_lshlrev_b64 v[116:117], 6, v[206:207]
	v_lshl_add_u64 v[116:117], s[22:23], 0, v[116:117]
	v_lshl_add_u64 v[116:117], s[38:39], 2, v[116:117]
	s_lshl_b32 s18, s55, 2
	v_lshl_add_u64 v[116:117], v[116:117], 0, s[18:19]
	s_waitcnt lgkmcnt(0)
	v_add_f32_e32 v114, v114, v115
	global_store_dword v[116:117], v114, off
; __device__ __forceinline__ u32x4 pack8(const f32x4 a, const f32x4 b) { u32x4 w; w.x = cvtpk(a[0], a[1]); w.y = cvtpk(a[2], a[3]); w.z = cvtpk(b[0], b[1]); w.w = cvtpk(b[2], b[3]); return w; }
; __device__ __forceinline__ void unpack8(const u32x4 w, f32x4& a, f32x4& b) { a = (f32x4){bflo(w.x), bfhi(w.x), bflo(w.y), bfhi(w.y)}; b = (f32x4){bflo(w.z), bfhi(w.z), bflo(w.w), bfhi(w.w)}; }
;     __device__ __forceinline__ void operator()(const Acc& acc, const Unit& u, int wr, int wc, int fr, int fq) const {
;     ...
;             for (int m = 0; m < 4; ++m) {
;                 const int row = u.pm * BM + ai * HALF + wr * 64 + m * 16 + fr; float s = 0.f;
; #pragma unroll
;                 for (int bj = 0; bj < 2; ++bj) {
;                     const size_t off = off0 + (size_t)(ai * HALF + m * 16) * D + bj * HALF;
;                     f32x4 b0, b1; unpack8(bw[ai][m][bj], b0, b1);
;                     const f32x4 v0 = b0 + acc[ai][bj][m][0] * scale, v1 = b1 + acc[ai][bj][m][1] * scale;
;                     s += (v0[0] * v0[0] + v0[1] * v0[1]) + (v0[2] * v0[2] + v0[3] * v0[3]) + (v1[0] * v1[0] + v1[1] * v1[1]) + (v1[2] * v1[2] + v1[3] * v1[3]);
;                     if (OUT_F32) { *(f32x4*)(outf + off) = v0; *(f32x4*)(outf + off + 4) = v1; }
;                     if (OUT_BF16) *(u32x4*)(outb + off) = pack8(v0, v1);
;                 }
;                 s += __shfl_xor(s, 16); s += __shfl_xor(s, 32);
;                 if (fq == 0) ssq[(size_t)row * 16 + u.pn * 4 + wc] = s;
;             }
.LBB0_683:
	s_or_b64 exec, exec, s[40:41]
	s_waitcnt vmcnt(14)
	v_lshlrev_b32_e32 v122, 16, v182
	v_and_b32_e32 v123, 0xffff0000, v182
	v_lshlrev_b32_e32 v124, 16, v183
	v_and_b32_e32 v125, 0xffff0000, v183
	v_lshlrev_b32_e32 v130, 16, v184
	v_and_b32_e32 v131, 0xffff0000, v184
	v_lshlrev_b32_e32 v132, 16, v185
	v_and_b32_e32 v133, 0xffff0000, v185
	v_pk_fma_f32 v[112:113], v[112:113], 0.5, v[124:125] op_sel_hi:[1,0,1]
	v_pk_fma_f32 v[110:111], v[110:111], 0.5, v[122:123] op_sel_hi:[1,0,1]
	v_pk_fma_f32 v[122:123], v[108:109], 0.5, v[132:133] op_sel_hi:[1,0,1]
	v_pk_fma_f32 v[108:109], v[106:107], 0.5, v[130:131] op_sel_hi:[1,0,1]
	v_mul_f32_e32 v106, v111, v111
	v_mul_f32_e32 v107, v113, v113
	v_fmac_f32_e32 v106, v110, v110
	v_fmac_f32_e32 v107, v112, v112
	v_add_f32_e32 v106, v106, v107
	v_mul_f32_e32 v107, v109, v109
	v_fmac_f32_e32 v107, v108, v108
	v_add_f32_e32 v106, v107, v106
	v_mul_f32_e32 v107, v123, v123
	v_fmac_f32_e32 v107, v122, v122
	v_add_f32_e32 v132, v107, v106
	v_cvt_pk_bf16_f32 v106, v110, v111
	v_cvt_pk_bf16_f32 v107, v112, v113
	v_lshlrev_b32_e32 v110, 16, v178
	v_and_b32_e32 v111, 0xffff0000, v178
	v_lshlrev_b32_e32 v112, 16, v179
	v_and_b32_e32 v113, 0xffff0000, v179
	v_lshlrev_b32_e32 v124, 16, v180
	v_and_b32_e32 v125, 0xffff0000, v180
	v_pk_fma_f32 v[104:105], v[104:105], 0.5, v[112:113] op_sel_hi:[1,0,1]
	v_pk_fma_f32 v[102:103], v[102:103], 0.5, v[110:111] op_sel_hi:[1,0,1]
	v_pk_fma_f32 v[112:113], v[98:99], 0.5, v[124:125] op_sel_hi:[1,0,1]
	v_mul_f32_e32 v98, v103, v103
	v_mul_f32_e32 v99, v105, v105
	v_fmac_f32_e32 v98, v102, v102
	v_fmac_f32_e32 v99, v104, v104
	v_lshlrev_b32_e32 v130, 16, v181
	v_and_b32_e32 v131, 0xffff0000, v181
	v_add_f32_e32 v98, v98, v99
	v_mul_f32_e32 v99, v113, v113
	v_pk_fma_f32 v[110:111], v[100:101], 0.5, v[130:131] op_sel_hi:[1,0,1]
	v_fmac_f32_e32 v99, v112, v112
	v_add_f32_e32 v98, v99, v98
	v_mul_f32_e32 v99, v111, v111
	v_fmac_f32_e32 v99, v110, v110
	v_add_f32_e32 v98, v99, v98
	v_add_f32_e32 v98, v132, v98
	v_mov_b32_e32 v99, v98
	s_nop 1
	v_permlane16_swap_b32_e32 v98, v99
	s_mov_b64 s[40:41], 0x8000
	s_waitcnt lgkmcnt(1)
	v_lshl_add_u64 v[114:115], v[208:209], 0, s[40:41]
	s_mov_b64 s[40:41], 0x8100
	v_lshl_add_u64 v[116:117], v[208:209], 0, s[40:41]
	s_waitcnt lgkmcnt(0)
	v_add_f32_e32 v98, v98, v99
	v_mov_b32_e32 v99, v98
	s_nop 1
	v_permlane32_swap_b32_e32 v98, v99
	v_cvt_pk_bf16_f32 v108, v108, v109
	v_cvt_pk_bf16_f32 v109, v122, v123
	v_cvt_pk_bf16_f32 v100, v102, v103
	v_cvt_pk_bf16_f32 v101, v104, v105
	v_cvt_pk_bf16_f32 v102, v112, v113
	v_cvt_pk_bf16_f32 v103, v110, v111
	global_store_dwordx4 v[114:115], v[106:109], off
	global_store_dwordx4 v[116:117], v[100:103], off
	s_and_saveexec_b64 s[40:41], s[4:5]
	s_cbranch_execz .LBB0_685
	v_or_b32_e32 v100, 16, v206
	v_ashrrev_i32_e32 v101, 31, v100
	s_waitcnt lgkmcnt(0)
	v_add_f32_e32 v102, v98, v99
	v_lshlrev_b64 v[98:99], 6, v[100:101]
	v_lshl_add_u64 v[98:99], s[22:23], 0, v[98:99]
	v_lshl_add_u64 v[98:99], s[38:39], 2, v[98:99]
	s_lshl_b32 s18, s55, 2
	v_lshl_add_u64 v[98:99], v[98:99], 0, s[18:19]
	global_store_dword v[98:99], v102, off
.LBB0_685:
	s_or_b64 exec, exec, s[40:41]
	s_waitcnt vmcnt(14)
	v_lshlrev_b32_e32 v102, 16, v174
	v_and_b32_e32 v103, 0xffff0000, v174
	v_lshlrev_b32_e32 v104, 16, v175
	v_and_b32_e32 v105, 0xffff0000, v175
	v_lshlrev_b32_e32 v106, 16, v176
	v_and_b32_e32 v107, 0xffff0000, v176
	v_lshlrev_b32_e32 v108, 16, v177
	v_and_b32_e32 v109, 0xffff0000, v177
	v_pk_fma_f32 v[96:97], v[96:97], 0.5, v[104:105] op_sel_hi:[1,0,1]
	v_pk_fma_f32 v[94:95], v[94:95], 0.5, v[102:103] op_sel_hi:[1,0,1]
	v_pk_fma_f32 v[102:103], v[92:93], 0.5, v[108:109] op_sel_hi:[1,0,1]
	v_pk_fma_f32 v[92:93], v[90:91], 0.5, v[106:107] op_sel_hi:[1,0,1]
	v_mul_f32_e32 v90, v95, v95
	v_mul_f32_e32 v91, v97, v97
	v_fmac_f32_e32 v90, v94, v94
	v_fmac_f32_e32 v91, v96, v96
	v_add_f32_e32 v90, v90, v91
	v_mul_f32_e32 v91, v93, v93
	v_fmac_f32_e32 v91, v92, v92
	v_add_f32_e32 v90, v91, v90
	v_mul_f32_e32 v91, v103, v103
	v_fmac_f32_e32 v91, v102, v102
	v_add_f32_e32 v108, v91, v90
	v_cvt_pk_bf16_f32 v90, v94, v95
	v_cvt_pk_bf16_f32 v91, v96, v97
	v_lshlrev_b32_e32 v94, 16, v170
	v_and_b32_e32 v95, 0xffff0000, v170
	v_lshlrev_b32_e32 v96, 16, v171
	v_and_b32_e32 v97, 0xffff0000, v171
	v_lshlrev_b32_e32 v104, 16, v172
	v_and_b32_e32 v105, 0xffff0000, v172
	v_pk_fma_f32 v[88:89], v[88:89], 0.5, v[96:97] op_sel_hi:[1,0,1]
	v_pk_fma_f32 v[86:87], v[86:87], 0.5, v[94:95] op_sel_hi:[1,0,1]
	v_pk_fma_f32 v[96:97], v[82:83], 0.5, v[104:105] op_sel_hi:[1,0,1]
	v_mul_f32_e32 v82, v87, v87
	v_mul_f32_e32 v83, v89, v89
	v_fmac_f32_e32 v82, v86, v86
	v_fmac_f32_e32 v83, v88, v88
	v_lshlrev_b32_e32 v106, 16, v173
	v_and_b32_e32 v107, 0xffff0000, v173
	v_add_f32_e32 v82, v82, v83
	v_mul_f32_e32 v83, v97, v97
	v_pk_fma_f32 v[94:95], v[84:85], 0.5, v[106:107] op_sel_hi:[1,0,1]
	v_fmac_f32_e32 v83, v96, v96
	v_add_f32_e32 v82, v83, v82
	v_mul_f32_e32 v83, v95, v95
	v_fmac_f32_e32 v83, v94, v94
	v_add_f32_e32 v82, v83, v82
	v_add_f32_e32 v82, v108, v82
	v_mov_b32_e32 v83, v82
	s_nop 1
	v_permlane16_swap_b32_e32 v82, v83
	s_mov_b64 s[40:41], 0x10000
	s_waitcnt lgkmcnt(1)
	v_lshl_add_u64 v[98:99], v[208:209], 0, s[40:41]
	s_mov_b64 s[40:41], 0x10100
	v_lshl_add_u64 v[100:101], v[208:209], 0, s[40:41]
	s_waitcnt lgkmcnt(0)
	v_add_f32_e32 v82, v82, v83
	v_mov_b32_e32 v83, v82
	s_nop 1
	v_permlane32_swap_b32_e32 v82, v83
	v_cvt_pk_bf16_f32 v92, v92, v93
	v_cvt_pk_bf16_f32 v93, v102, v103
	v_cvt_pk_bf16_f32 v84, v86, v87
	v_cvt_pk_bf16_f32 v85, v88, v89
	v_cvt_pk_bf16_f32 v86, v96, v97
	v_cvt_pk_bf16_f32 v87, v94, v95
	global_store_dwordx4 v[98:99], v[90:93], off
	global_store_dwordx4 v[100:101], v[84:87], off
	s_and_saveexec_b64 s[40:41], s[4:5]
	s_cbranch_execz .LBB0_687
	v_or_b32_e32 v84, 32, v206
	v_ashrrev_i32_e32 v85, 31, v84
	s_waitcnt lgkmcnt(0)
	v_add_f32_e32 v86, v82, v83
	v_lshlrev_b64 v[82:83], 6, v[84:85]
	v_lshl_add_u64 v[82:83], s[22:23], 0, v[82:83]
	v_lshl_add_u64 v[82:83], s[38:39], 2, v[82:83]
	s_lshl_b32 s18, s55, 2
	v_lshl_add_u64 v[82:83], v[82:83], 0, s[18:19]
	global_store_dword v[82:83], v86, off
; __device__ __forceinline__ u32x4 pack8(const f32x4 a, const f32x4 b) { u32x4 w; w.x = cvtpk(a[0], a[1]); w.y = cvtpk(a[2], a[3]); w.z = cvtpk(b[0], b[1]); w.w = cvtpk(b[2], b[3]); return w; }
; __device__ __forceinline__ void unpack8(const u32x4 w, f32x4& a, f32x4& b) { a = (f32x4){bflo(w.x), bfhi(w.x), bflo(w.y), bfhi(w.y)}; b = (f32x4){bflo(w.z), bfhi(w.z), bflo(w.w), bfhi(w.w)}; }
;     __device__ __forceinline__ void operator()(const Acc& acc, const Unit& u, int wr, int wc, int fr, int fq) const {
;     ...
;             for (int m = 0; m < 4; ++m) {
;                 const int row = u.pm * BM + ai * HALF + wr * 64 + m * 16 + fr; float s = 0.f;
; #pragma unroll
;                 for (int bj = 0; bj < 2; ++bj) {
;                     const size_t off = off0 + (size_t)(ai * HALF + m * 16) * D + bj * HALF;
;                     f32x4 b0, b1; unpack8(bw[ai][m][bj], b0, b1);
;                     const f32x4 v0 = b0 + acc[ai][bj][m][0] * scale, v1 = b1 + acc[ai][bj][m][1] * scale;
;                     s += (v0[0] * v0[0] + v0[1] * v0[1]) + (v0[2] * v0[2] + v0[3] * v0[3]) + (v1[0] * v1[0] + v1[1] * v1[1]) + (v1[2] * v1[2] + v1[3] * v1[3]);
;                     if (OUT_F32) { *(f32x4*)(outf + off) = v0; *(f32x4*)(outf + off + 4) = v1; }
;                     if (OUT_BF16) *(u32x4*)(outb + off) = pack8(v0, v1);
;                 }
;                 s += __shfl_xor(s, 16); s += __shfl_xor(s, 32);
;                 if (fq == 0) ssq[(size_t)row * 16 + u.pn * 4 + wc] = s;
;             }
.LBB0_687:
	s_or_b64 exec, exec, s[40:41]
	s_waitcnt vmcnt(14)
	v_lshlrev_b32_e32 v86, 16, v166
	v_and_b32_e32 v87, 0xffff0000, v166
	v_lshlrev_b32_e32 v88, 16, v167
	v_and_b32_e32 v89, 0xffff0000, v167
	v_lshlrev_b32_e32 v90, 16, v168
	v_and_b32_e32 v91, 0xffff0000, v168
	v_lshlrev_b32_e32 v92, 16, v169
	v_and_b32_e32 v93, 0xffff0000, v169
	v_pk_fma_f32 v[80:81], v[80:81], 0.5, v[88:89] op_sel_hi:[1,0,1]
	v_pk_fma_f32 v[78:79], v[78:79], 0.5, v[86:87] op_sel_hi:[1,0,1]
	v_pk_fma_f32 v[86:87], v[76:77], 0.5, v[92:93] op_sel_hi:[1,0,1]
	v_pk_fma_f32 v[76:77], v[74:75], 0.5, v[90:91] op_sel_hi:[1,0,1]
	v_mul_f32_e32 v74, v79, v79
	v_mul_f32_e32 v75, v81, v81
	v_fmac_f32_e32 v74, v78, v78
	v_fmac_f32_e32 v75, v80, v80
	v_add_f32_e32 v74, v74, v75
	v_mul_f32_e32 v75, v77, v77
	v_fmac_f32_e32 v75, v76, v76
	v_add_f32_e32 v74, v75, v74
	v_mul_f32_e32 v75, v87, v87
	v_fmac_f32_e32 v75, v86, v86
	v_add_f32_e32 v92, v75, v74
	v_cvt_pk_bf16_f32 v74, v78, v79
	v_cvt_pk_bf16_f32 v75, v80, v81
	v_lshlrev_b32_e32 v78, 16, v162
	v_and_b32_e32 v79, 0xffff0000, v162
	v_lshlrev_b32_e32 v80, 16, v163
	v_and_b32_e32 v81, 0xffff0000, v163
	v_lshlrev_b32_e32 v88, 16, v164
	v_and_b32_e32 v89, 0xffff0000, v164
	v_pk_fma_f32 v[72:73], v[72:73], 0.5, v[80:81] op_sel_hi:[1,0,1]
	v_pk_fma_f32 v[70:71], v[70:71], 0.5, v[78:79] op_sel_hi:[1,0,1]
	v_pk_fma_f32 v[80:81], v[66:67], 0.5, v[88:89] op_sel_hi:[1,0,1]
	v_mul_f32_e32 v66, v71, v71
	v_mul_f32_e32 v67, v73, v73
	v_fmac_f32_e32 v66, v70, v70
	v_fmac_f32_e32 v67, v72, v72
	v_lshlrev_b32_e32 v90, 16, v165
	v_and_b32_e32 v91, 0xffff0000, v165
	v_add_f32_e32 v66, v66, v67
	v_mul_f32_e32 v67, v81, v81
	v_pk_fma_f32 v[78:79], v[68:69], 0.5, v[90:91] op_sel_hi:[1,0,1]
	v_fmac_f32_e32 v67, v80, v80
	v_add_f32_e32 v66, v67, v66
	v_mul_f32_e32 v67, v79, v79
	v_fmac_f32_e32 v67, v78, v78
	v_add_f32_e32 v66, v67, v66
	v_add_f32_e32 v66, v92, v66
	v_mov_b32_e32 v67, v66
	s_nop 1
	v_permlane16_swap_b32_e32 v66, v67
	s_mov_b64 s[40:41], 0x18000
	s_waitcnt lgkmcnt(1)
	v_lshl_add_u64 v[82:83], v[208:209], 0, s[40:41]
	s_mov_b64 s[40:41], 0x18100
	v_lshl_add_u64 v[84:85], v[208:209], 0, s[40:41]
	s_waitcnt lgkmcnt(0)
	v_add_f32_e32 v66, v66, v67
	v_mov_b32_e32 v67, v66
	s_nop 1
	v_permlane32_swap_b32_e32 v66, v67
	v_cvt_pk_bf16_f32 v76, v76, v77
	v_cvt_pk_bf16_f32 v77, v86, v87
	v_cvt_pk_bf16_f32 v68, v70, v71
	v_cvt_pk_bf16_f32 v69, v72, v73
	v_cvt_pk_bf16_f32 v70, v80, v81
	v_cvt_pk_bf16_f32 v71, v78, v79
	global_store_dwordx4 v[82:83], v[74:77], off
	global_store_dwordx4 v[84:85], v[68:71], off
	s_and_saveexec_b64 s[40:41], s[4:5]
	s_cbranch_execz .LBB0_689
	v_or_b32_e32 v68, 48, v206
	v_ashrrev_i32_e32 v69, 31, v68
	s_waitcnt lgkmcnt(0)
	v_add_f32_e32 v70, v66, v67
	v_lshlrev_b64 v[66:67], 6, v[68:69]
	v_lshl_add_u64 v[66:67], s[22:23], 0, v[66:67]
	v_lshl_add_u64 v[66:67], s[38:39], 2, v[66:67]
	s_lshl_b32 s18, s55, 2
	v_lshl_add_u64 v[66:67], v[66:67], 0, s[18:19]
	global_store_dword v[66:67], v70, off
.LBB0_689:
	s_or_b64 exec, exec, s[40:41]
	s_waitcnt vmcnt(14)
	v_lshlrev_b32_e32 v70, 16, v158
	v_and_b32_e32 v71, 0xffff0000, v158
	v_lshlrev_b32_e32 v72, 16, v159
	v_and_b32_e32 v73, 0xffff0000, v159
	v_lshlrev_b32_e32 v74, 16, v160
	v_and_b32_e32 v75, 0xffff0000, v160
	v_lshlrev_b32_e32 v76, 16, v161
	v_and_b32_e32 v77, 0xffff0000, v161
	v_pk_fma_f32 v[64:65], v[64:65], 0.5, v[72:73] op_sel_hi:[1,0,1]
	v_pk_fma_f32 v[62:63], v[62:63], 0.5, v[70:71] op_sel_hi:[1,0,1]
	v_pk_fma_f32 v[70:71], v[60:61], 0.5, v[76:77] op_sel_hi:[1,0,1]
	v_pk_fma_f32 v[60:61], v[58:59], 0.5, v[74:75] op_sel_hi:[1,0,1]
	v_mul_f32_e32 v58, v63, v63
	v_mul_f32_e32 v59, v65, v65
	v_fmac_f32_e32 v58, v62, v62
	v_fmac_f32_e32 v59, v64, v64
	v_add_f32_e32 v58, v58, v59
	v_mul_f32_e32 v59, v61, v61
	v_fmac_f32_e32 v59, v60, v60
	v_add_f32_e32 v58, v59, v58
	v_mul_f32_e32 v59, v71, v71
	v_fmac_f32_e32 v59, v70, v70
	v_add_f32_e32 v76, v59, v58
	v_cvt_pk_bf16_f32 v58, v62, v63
	v_cvt_pk_bf16_f32 v59, v64, v65
	v_lshlrev_b32_e32 v62, 16, v154
	v_and_b32_e32 v63, 0xffff0000, v154
	v_lshlrev_b32_e32 v64, 16, v155
	v_and_b32_e32 v65, 0xffff0000, v155
	v_lshlrev_b32_e32 v72, 16, v156
	v_and_b32_e32 v73, 0xffff0000, v156
	v_pk_fma_f32 v[56:57], v[56:57], 0.5, v[64:65] op_sel_hi:[1,0,1]
	v_pk_fma_f32 v[54:55], v[54:55], 0.5, v[62:63] op_sel_hi:[1,0,1]
	v_pk_fma_f32 v[64:65], v[50:51], 0.5, v[72:73] op_sel_hi:[1,0,1]
	v_mul_f32_e32 v50, v55, v55
	v_mul_f32_e32 v51, v57, v57
	v_fmac_f32_e32 v50, v54, v54
	v_fmac_f32_e32 v51, v56, v56
	v_lshlrev_b32_e32 v74, 16, v157
	v_and_b32_e32 v75, 0xffff0000, v157
	v_add_f32_e32 v50, v50, v51
	v_mul_f32_e32 v51, v65, v65
	v_pk_fma_f32 v[62:63], v[52:53], 0.5, v[74:75] op_sel_hi:[1,0,1]
	v_fmac_f32_e32 v51, v64, v64
	v_add_f32_e32 v50, v51, v50
	v_mul_f32_e32 v51, v63, v63
	v_fmac_f32_e32 v51, v62, v62
	v_add_f32_e32 v50, v51, v50
	v_add_f32_e32 v50, v76, v50
	v_mov_b32_e32 v51, v50
	s_nop 1
	v_permlane16_swap_b32_e32 v50, v51
	s_mov_b64 s[40:41], 0x40000
	s_waitcnt lgkmcnt(1)
	v_lshl_add_u64 v[66:67], v[208:209], 0, s[40:41]
	s_mov_b64 s[40:41], 0x40100
	v_lshl_add_u64 v[68:69], v[208:209], 0, s[40:41]
	s_waitcnt lgkmcnt(0)
	v_add_f32_e32 v50, v50, v51
	v_mov_b32_e32 v51, v50
	s_nop 1
	v_permlane32_swap_b32_e32 v50, v51
	v_cvt_pk_bf16_f32 v60, v60, v61
	v_cvt_pk_bf16_f32 v61, v70, v71
	v_cvt_pk_bf16_f32 v52, v54, v55
	v_cvt_pk_bf16_f32 v53, v56, v57
	v_cvt_pk_bf16_f32 v54, v64, v65
	v_cvt_pk_bf16_f32 v55, v62, v63
	global_store_dwordx4 v[66:67], v[58:61], off
	global_store_dwordx4 v[68:69], v[52:55], off
	s_and_saveexec_b64 s[40:41], s[4:5]
	s_cbranch_execz .LBB0_691
	v_add_u32_e32 v52, 0x80, v206
	v_ashrrev_i32_e32 v53, 31, v52
	s_waitcnt lgkmcnt(0)
	v_add_f32_e32 v54, v50, v51
	v_lshlrev_b64 v[50:51], 6, v[52:53]
	v_lshl_add_u64 v[50:51], s[22:23], 0, v[50:51]
	v_lshl_add_u64 v[50:51], s[38:39], 2, v[50:51]
	s_lshl_b32 s18, s55, 2
	v_lshl_add_u64 v[50:51], v[50:51], 0, s[18:19]
	global_store_dword v[50:51], v54, off
; __device__ __forceinline__ u32x4 pack8(const f32x4 a, const f32x4 b) { u32x4 w; w.x = cvtpk(a[0], a[1]); w.y = cvtpk(a[2], a[3]); w.z = cvtpk(b[0], b[1]); w.w = cvtpk(b[2], b[3]); return w; }
; __device__ __forceinline__ void unpack8(const u32x4 w, f32x4& a, f32x4& b) { a = (f32x4){bflo(w.x), bfhi(w.x), bflo(w.y), bfhi(w.y)}; b = (f32x4){bflo(w.z), bfhi(w.z), bflo(w.w), bfhi(w.w)}; }
;     __device__ __forceinline__ void operator()(const Acc& acc, const Unit& u, int wr, int wc, int fr, int fq) const {
;     ...
;             for (int m = 0; m < 4; ++m) {
;                 const int row = u.pm * BM + ai * HALF + wr * 64 + m * 16 + fr; float s = 0.f;
; #pragma unroll
;                 for (int bj = 0; bj < 2; ++bj) {
;                     const size_t off = off0 + (size_t)(ai * HALF + m * 16) * D + bj * HALF;
;                     f32x4 b0, b1; unpack8(bw[ai][m][bj], b0, b1);
;                     const f32x4 v0 = b0 + acc[ai][bj][m][0] * scale, v1 = b1 + acc[ai][bj][m][1] * scale;
;                     s += (v0[0] * v0[0] + v0[1] * v0[1]) + (v0[2] * v0[2] + v0[3] * v0[3]) + (v1[0] * v1[0] + v1[1] * v1[1]) + (v1[2] * v1[2] + v1[3] * v1[3]);
;                     if (OUT_F32) { *(f32x4*)(outf + off) = v0; *(f32x4*)(outf + off + 4) = v1; }
;                     if (OUT_BF16) *(u32x4*)(outb + off) = pack8(v0, v1);
;                 }
;                 s += __shfl_xor(s, 16); s += __shfl_xor(s, 32);
;                 if (fq == 0) ssq[(size_t)row * 16 + u.pn * 4 + wc] = s;
;             }
.LBB0_691:
	s_or_b64 exec, exec, s[40:41]
	s_waitcnt vmcnt(14)
	v_lshlrev_b32_e32 v54, 16, v150
	v_and_b32_e32 v55, 0xffff0000, v150
	v_lshlrev_b32_e32 v56, 16, v151
	v_and_b32_e32 v57, 0xffff0000, v151
	v_lshlrev_b32_e32 v58, 16, v152
	v_and_b32_e32 v59, 0xffff0000, v152
	v_lshlrev_b32_e32 v60, 16, v153
	v_and_b32_e32 v61, 0xffff0000, v153
	v_pk_fma_f32 v[48:49], v[48:49], 0.5, v[56:57] op_sel_hi:[1,0,1]
	v_pk_fma_f32 v[46:47], v[46:47], 0.5, v[54:55] op_sel_hi:[1,0,1]
	v_pk_fma_f32 v[54:55], v[44:45], 0.5, v[60:61] op_sel_hi:[1,0,1]
	v_pk_fma_f32 v[44:45], v[42:43], 0.5, v[58:59] op_sel_hi:[1,0,1]
	v_mul_f32_e32 v42, v47, v47
	v_mul_f32_e32 v43, v49, v49
	v_fmac_f32_e32 v42, v46, v46
	v_fmac_f32_e32 v43, v48, v48
	v_add_f32_e32 v42, v42, v43
	v_mul_f32_e32 v43, v45, v45
	v_fmac_f32_e32 v43, v44, v44
	v_add_f32_e32 v42, v43, v42
	v_mul_f32_e32 v43, v55, v55
	v_fmac_f32_e32 v43, v54, v54
	v_add_f32_e32 v60, v43, v42
	v_cvt_pk_bf16_f32 v42, v46, v47
	v_cvt_pk_bf16_f32 v43, v48, v49
	v_lshlrev_b32_e32 v46, 16, v146
	v_and_b32_e32 v47, 0xffff0000, v146
	v_lshlrev_b32_e32 v48, 16, v147
	v_and_b32_e32 v49, 0xffff0000, v147
	v_lshlrev_b32_e32 v56, 16, v148
	v_and_b32_e32 v57, 0xffff0000, v148
	v_pk_fma_f32 v[40:41], v[40:41], 0.5, v[48:49] op_sel_hi:[1,0,1]
	v_pk_fma_f32 v[38:39], v[38:39], 0.5, v[46:47] op_sel_hi:[1,0,1]
	v_pk_fma_f32 v[48:49], v[34:35], 0.5, v[56:57] op_sel_hi:[1,0,1]
	v_mul_f32_e32 v34, v39, v39
	v_mul_f32_e32 v35, v41, v41
	v_fmac_f32_e32 v34, v38, v38
	v_fmac_f32_e32 v35, v40, v40
	v_lshlrev_b32_e32 v58, 16, v149
	v_and_b32_e32 v59, 0xffff0000, v149
	v_add_f32_e32 v34, v34, v35
	v_mul_f32_e32 v35, v49, v49
	v_pk_fma_f32 v[46:47], v[36:37], 0.5, v[58:59] op_sel_hi:[1,0,1]
	v_fmac_f32_e32 v35, v48, v48
	v_add_f32_e32 v34, v35, v34
	v_mul_f32_e32 v35, v47, v47
	v_fmac_f32_e32 v35, v46, v46
	v_add_f32_e32 v34, v35, v34
	v_add_f32_e32 v34, v60, v34
	v_mov_b32_e32 v35, v34
	s_nop 1
	v_permlane16_swap_b32_e32 v34, v35
	s_mov_b64 s[40:41], 0x48000
	s_waitcnt lgkmcnt(1)
	v_lshl_add_u64 v[50:51], v[208:209], 0, s[40:41]
	s_mov_b64 s[40:41], 0x48100
	v_lshl_add_u64 v[52:53], v[208:209], 0, s[40:41]
	s_waitcnt lgkmcnt(0)
	v_add_f32_e32 v34, v34, v35
	v_mov_b32_e32 v35, v34
	s_nop 1
	v_permlane32_swap_b32_e32 v34, v35
	v_cvt_pk_bf16_f32 v44, v44, v45
	v_cvt_pk_bf16_f32 v45, v54, v55
	v_cvt_pk_bf16_f32 v36, v38, v39
	v_cvt_pk_bf16_f32 v37, v40, v41
	v_cvt_pk_bf16_f32 v38, v48, v49
	v_cvt_pk_bf16_f32 v39, v46, v47
	global_store_dwordx4 v[50:51], v[42:45], off
	global_store_dwordx4 v[52:53], v[36:39], off
	s_and_saveexec_b64 s[40:41], s[4:5]
	s_cbranch_execz .LBB0_693
	v_add_u32_e32 v36, 0x90, v206
	v_ashrrev_i32_e32 v37, 31, v36
	s_waitcnt lgkmcnt(0)
	v_add_f32_e32 v38, v34, v35
	v_lshlrev_b64 v[34:35], 6, v[36:37]
	v_lshl_add_u64 v[34:35], s[22:23], 0, v[34:35]
	v_lshl_add_u64 v[34:35], s[38:39], 2, v[34:35]
	s_lshl_b32 s18, s55, 2
	v_lshl_add_u64 v[34:35], v[34:35], 0, s[18:19]
	global_store_dword v[34:35], v38, off
; __device__ __forceinline__ u32x4 pack8(const f32x4 a, const f32x4 b) { u32x4 w; w.x = cvtpk(a[0], a[1]); w.y = cvtpk(a[2], a[3]); w.z = cvtpk(b[0], b[1]); w.w = cvtpk(b[2], b[3]); return w; }
; __device__ __forceinline__ void unpack8(const u32x4 w, f32x4& a, f32x4& b) { a = (f32x4){bflo(w.x), bfhi(w.x), bflo(w.y), bfhi(w.y)}; b = (f32x4){bflo(w.z), bfhi(w.z), bflo(w.w), bfhi(w.w)}; }
;     __device__ __forceinline__ void operator()(const Acc& acc, const Unit& u, int wr, int wc, int fr, int fq) const {
;     ...
;             for (int m = 0; m < 4; ++m) {
;                 const int row = u.pm * BM + ai * HALF + wr * 64 + m * 16 + fr; float s = 0.f;
; #pragma unroll
;                 for (int bj = 0; bj < 2; ++bj) {
;                     const size_t off = off0 + (size_t)(ai * HALF + m * 16) * D + bj * HALF;
;                     f32x4 b0, b1; unpack8(bw[ai][m][bj], b0, b1);
;                     const f32x4 v0 = b0 + acc[ai][bj][m][0] * scale, v1 = b1 + acc[ai][bj][m][1] * scale;
;                     s += (v0[0] * v0[0] + v0[1] * v0[1]) + (v0[2] * v0[2] + v0[3] * v0[3]) + (v1[0] * v1[0] + v1[1] * v1[1]) + (v1[2] * v1[2] + v1[3] * v1[3]);
;                     if (OUT_F32) { *(f32x4*)(outf + off) = v0; *(f32x4*)(outf + off + 4) = v1; }
;                     if (OUT_BF16) *(u32x4*)(outb + off) = pack8(v0, v1);
;                 }
;                 s += __shfl_xor(s, 16); s += __shfl_xor(s, 32);
;                 if (fq == 0) ssq[(size_t)row * 16 + u.pn * 4 + wc] = s;
;             }
.LBB0_693:
	s_or_b64 exec, exec, s[40:41]
	s_waitcnt vmcnt(14)
	v_lshlrev_b32_e32 v38, 16, v142
	v_and_b32_e32 v39, 0xffff0000, v142
	v_lshlrev_b32_e32 v40, 16, v143
	v_and_b32_e32 v41, 0xffff0000, v143
	v_lshlrev_b32_e32 v42, 16, v144
	v_and_b32_e32 v43, 0xffff0000, v144
	v_lshlrev_b32_e32 v44, 16, v145
	v_and_b32_e32 v45, 0xffff0000, v145
	v_pk_fma_f32 v[32:33], v[32:33], 0.5, v[40:41] op_sel_hi:[1,0,1]
	v_pk_fma_f32 v[30:31], v[30:31], 0.5, v[38:39] op_sel_hi:[1,0,1]
	v_pk_fma_f32 v[38:39], v[28:29], 0.5, v[44:45] op_sel_hi:[1,0,1]
	v_pk_fma_f32 v[28:29], v[26:27], 0.5, v[42:43] op_sel_hi:[1,0,1]
	v_mul_f32_e32 v26, v31, v31
	v_mul_f32_e32 v27, v33, v33
	v_fmac_f32_e32 v26, v30, v30
	v_fmac_f32_e32 v27, v32, v32
	v_add_f32_e32 v26, v26, v27
	v_mul_f32_e32 v27, v29, v29
	v_fmac_f32_e32 v27, v28, v28
	v_add_f32_e32 v26, v27, v26
	v_mul_f32_e32 v27, v39, v39
	v_fmac_f32_e32 v27, v38, v38
	v_add_f32_e32 v44, v27, v26
	v_cvt_pk_bf16_f32 v26, v30, v31
	v_cvt_pk_bf16_f32 v27, v32, v33
	v_lshlrev_b32_e32 v30, 16, v138
	v_and_b32_e32 v31, 0xffff0000, v138
	v_lshlrev_b32_e32 v32, 16, v139
	v_and_b32_e32 v33, 0xffff0000, v139
	v_lshlrev_b32_e32 v40, 16, v140
	v_and_b32_e32 v41, 0xffff0000, v140
	v_pk_fma_f32 v[24:25], v[24:25], 0.5, v[32:33] op_sel_hi:[1,0,1]
	v_pk_fma_f32 v[22:23], v[22:23], 0.5, v[30:31] op_sel_hi:[1,0,1]
	v_pk_fma_f32 v[32:33], v[18:19], 0.5, v[40:41] op_sel_hi:[1,0,1]
	v_mul_f32_e32 v18, v23, v23
	v_mul_f32_e32 v19, v25, v25
	v_fmac_f32_e32 v18, v22, v22
	v_fmac_f32_e32 v19, v24, v24
	v_lshlrev_b32_e32 v42, 16, v141
	v_and_b32_e32 v43, 0xffff0000, v141
	v_add_f32_e32 v18, v18, v19
	v_mul_f32_e32 v19, v33, v33
	v_pk_fma_f32 v[30:31], v[20:21], 0.5, v[42:43] op_sel_hi:[1,0,1]
	v_fmac_f32_e32 v19, v32, v32
	v_add_f32_e32 v18, v19, v18
	v_mul_f32_e32 v19, v31, v31
	v_fmac_f32_e32 v19, v30, v30
	v_add_f32_e32 v18, v19, v18
	v_add_f32_e32 v18, v44, v18
	v_mov_b32_e32 v19, v18
	s_nop 1
	v_permlane16_swap_b32_e32 v18, v19
	s_mov_b64 s[40:41], 0x50000
	s_waitcnt lgkmcnt(1)
	v_lshl_add_u64 v[34:35], v[208:209], 0, s[40:41]
	s_mov_b64 s[40:41], 0x50100
	v_lshl_add_u64 v[36:37], v[208:209], 0, s[40:41]
	s_waitcnt lgkmcnt(0)
	v_add_f32_e32 v18, v18, v19
	v_mov_b32_e32 v19, v18
	s_nop 1
	v_permlane32_swap_b32_e32 v18, v19
	v_cvt_pk_bf16_f32 v28, v28, v29
	v_cvt_pk_bf16_f32 v29, v38, v39
	v_cvt_pk_bf16_f32 v20, v22, v23
	v_cvt_pk_bf16_f32 v21, v24, v25
	v_cvt_pk_bf16_f32 v22, v32, v33
	v_cvt_pk_bf16_f32 v23, v30, v31
	global_store_dwordx4 v[34:35], v[26:29], off
	global_store_dwordx4 v[36:37], v[20:23], off
	s_and_saveexec_b64 s[40:41], s[4:5]
	s_cbranch_execz .LBB0_695
	v_add_u32_e32 v20, 0xa0, v206
	v_ashrrev_i32_e32 v21, 31, v20
	s_waitcnt lgkmcnt(0)
	v_add_f32_e32 v22, v18, v19
	v_lshlrev_b64 v[18:19], 6, v[20:21]
	v_lshl_add_u64 v[18:19], s[22:23], 0, v[18:19]
	v_lshl_add_u64 v[18:19], s[38:39], 2, v[18:19]
	s_lshl_b32 s18, s55, 2
	v_lshl_add_u64 v[18:19], v[18:19], 0, s[18:19]
	global_store_dword v[18:19], v22, off
.LBB0_695:
	s_or_b64 exec, exec, s[40:41]
	s_waitcnt vmcnt(14)
	v_lshlrev_b32_e32 v22, 16, v126
	v_and_b32_e32 v23, 0xffff0000, v126
	v_lshlrev_b32_e32 v24, 16, v127
	v_and_b32_e32 v25, 0xffff0000, v127
	v_lshlrev_b32_e32 v26, 16, v128
	v_and_b32_e32 v27, 0xffff0000, v128
	v_lshlrev_b32_e32 v28, 16, v129
	v_and_b32_e32 v29, 0xffff0000, v129
	v_pk_fma_f32 v[16:17], v[16:17], 0.5, v[24:25] op_sel_hi:[1,0,1]
	v_pk_fma_f32 v[14:15], v[14:15], 0.5, v[22:23] op_sel_hi:[1,0,1]
	v_pk_fma_f32 v[22:23], v[12:13], 0.5, v[28:29] op_sel_hi:[1,0,1]
	v_pk_fma_f32 v[12:13], v[10:11], 0.5, v[26:27] op_sel_hi:[1,0,1]
	v_mul_f32_e32 v10, v15, v15
	v_mul_f32_e32 v11, v17, v17
	v_fmac_f32_e32 v10, v14, v14
	v_fmac_f32_e32 v11, v16, v16
	v_add_f32_e32 v10, v10, v11
	v_mul_f32_e32 v11, v13, v13
	v_fmac_f32_e32 v11, v12, v12
	v_add_f32_e32 v10, v11, v10
	v_mul_f32_e32 v11, v23, v23
	v_fmac_f32_e32 v11, v22, v22
	v_add_f32_e32 v28, v11, v10
	v_cvt_pk_bf16_f32 v10, v14, v15
	v_cvt_pk_bf16_f32 v11, v16, v17
	v_lshlrev_b32_e32 v14, 16, v118
	v_and_b32_e32 v15, 0xffff0000, v118
	v_lshlrev_b32_e32 v16, 16, v119
	v_and_b32_e32 v17, 0xffff0000, v119
	v_lshlrev_b32_e32 v24, 16, v120
	v_and_b32_e32 v25, 0xffff0000, v120
	v_pk_fma_f32 v[8:9], v[8:9], 0.5, v[16:17] op_sel_hi:[1,0,1]
	v_pk_fma_f32 v[6:7], v[6:7], 0.5, v[14:15] op_sel_hi:[1,0,1]
	v_pk_fma_f32 v[16:17], v[2:3], 0.5, v[24:25] op_sel_hi:[1,0,1]
	v_mul_f32_e32 v2, v7, v7
	v_mul_f32_e32 v3, v9, v9
	v_fmac_f32_e32 v2, v6, v6
	v_fmac_f32_e32 v3, v8, v8
	v_lshlrev_b32_e32 v26, 16, v121
	v_and_b32_e32 v27, 0xffff0000, v121
	v_add_f32_e32 v2, v2, v3
	v_mul_f32_e32 v3, v17, v17
	v_pk_fma_f32 v[14:15], v[4:5], 0.5, v[26:27] op_sel_hi:[1,0,1]
	v_fmac_f32_e32 v3, v16, v16
	v_add_f32_e32 v2, v3, v2
	v_mul_f32_e32 v3, v15, v15
	v_fmac_f32_e32 v3, v14, v14
	v_add_f32_e32 v2, v3, v2
	v_add_f32_e32 v2, v28, v2
	v_mov_b32_e32 v3, v2
	s_nop 1
	v_permlane16_swap_b32_e32 v2, v3
	s_mov_b64 s[40:41], 0x58000
	s_waitcnt lgkmcnt(1)
	v_lshl_add_u64 v[18:19], v[208:209], 0, s[40:41]
	s_mov_b64 s[40:41], 0x58100
	v_lshl_add_u64 v[20:21], v[208:209], 0, s[40:41]
	s_waitcnt lgkmcnt(0)
	v_add_f32_e32 v2, v2, v3
	v_mov_b32_e32 v3, v2
	s_nop 1
	v_permlane32_swap_b32_e32 v2, v3
	v_cvt_pk_bf16_f32 v12, v12, v13
	v_cvt_pk_bf16_f32 v13, v22, v23
	v_cvt_pk_bf16_f32 v4, v6, v7
	v_cvt_pk_bf16_f32 v5, v8, v9
	v_cvt_pk_bf16_f32 v6, v16, v17
	v_cvt_pk_bf16_f32 v7, v14, v15
	global_store_dwordx4 v[18:19], v[10:13], off
	global_store_dwordx4 v[20:21], v[4:7], off
	s_and_saveexec_b64 s[40:41], s[4:5]
	s_cbranch_execz .LBB0_697
	v_add_u32_e32 v4, 0xb0, v206
	v_ashrrev_i32_e32 v5, 31, v4
	s_waitcnt lgkmcnt(0)
	v_add_f32_e32 v6, v2, v3
	v_lshlrev_b64 v[2:3], 6, v[4:5]
	v_lshl_add_u64 v[2:3], s[22:23], 0, v[2:3]
	v_lshl_add_u64 v[2:3], s[38:39], 2, v[2:3]
	s_lshl_b32 s18, s55, 2
	v_lshl_add_u64 v[2:3], v[2:3], 0, s[18:19]
	global_store_dword v[2:3], v6, off

; __device__ __forceinline__ u32x4 pack8(const f32x4 a, const f32x4 b) { u32x4 w; w.x = cvtpk(a[0], a[1]); w.y = cvtpk(a[2], a[3]); w.z = cvtpk(b[0], b[1]); w.w = cvtpk(b[2], b[3]); return w; }
; __device__ __forceinline__ void unpack8(const u32x4 w, f32x4& a, f32x4& b) { a = (f32x4){bflo(w.x), bfhi(w.x), bflo(w.y), bfhi(w.y)}; b = (f32x4){bflo(w.z), bfhi(w.z), bflo(w.w), bfhi(w.w)}; }
;     __device__ __forceinline__ void operator()(const Acc& acc, const Unit& u, int wr, int wc, int fr, int fq) const {
;         const size_t off0 = (size_t)(u.pm * BM + wr * 64 + fr) * D + u.pn * BM + wc * 32 + 8 * fq;
;         u32x4 bw[2][4][2];
; #pragma unroll
;         for (int ai = 0; ai < 2; ++ai)
; #pragma unroll
;             for (int m = 0; m < 4; ++m)
; #pragma unroll
;                 for (int bj = 0; bj < 2; ++bj) bw[ai][m][bj] = *(const u32x4*)((const bf16_t*)base + off0 + (size_t)(ai * HALF + m * 16) * D + bj * HALF);
; #pragma unroll
;         for (int ai = 0; ai < 2; ++ai)
; #pragma unroll
;             for (int m = 0; m < 4; ++m) {
;                 const int row = u.pm * BM + ai * HALF + wr * 64 + m * 16 + fr; float s = 0.f;
; #pragma unroll
;                 for (int bj = 0; bj < 2; ++bj) {
;                     const size_t off = off0 + (size_t)(ai * HALF + m * 16) * D + bj * HALF;
;                     f32x4 b0, b1; unpack8(bw[ai][m][bj], b0, b1);
;                     const f32x4 v0 = b0 + acc[ai][bj][m][0] * scale, v1 = b1 + acc[ai][bj][m][1] * scale;
;                     s += (v0[0] * v0[0] + v0[1] * v0[1]) + (v0[2] * v0[2] + v0[3] * v0[3]) + (v1[0] * v1[0] + v1[1] * v1[1]) + (v1[2] * v1[2] + v1[3] * v1[3]);
;                     if (OUT_F32) { *(f32x4*)(outf + off) = v0; *(f32x4*)(outf + off + 4) = v1; }
;                     if (OUT_BF16) *(u32x4*)(outb + off) = pack8(v0, v1);
;                 }
;                 s += __shfl_xor(s, 16); s += __shfl_xor(s, 32);
;                 if (fq == 0) ssq[(size_t)row * 16 + u.pn * 4 + wc] = s;
;             }
.LBB0_1579:
	v_lshl_add_u32 v206, s8, 8, v209
	v_ashrrev_i32_e32 v207, 31, v206
	s_lshl_b32 s8, s14, 8
	v_lshlrev_b64 v[106:107], 10, v[206:207]
	s_ashr_i32 s9, s8, 31
	v_lshl_add_u64 v[106:107], v[106:107], 0, s[8:9]
	v_or_b32_e32 v106, v106, v194
	v_lshlrev_b64 v[226:227], 1, v[106:107]
	v_lshl_add_u64 v[106:107], s[88:89], 0, v[226:227]
	global_load_dwordx4 v[218:221], v[106:107], off
	global_load_dwordx4 v[222:225], v[106:107], off offset:256
	v_add_co_u32_e64 v114, s[8:9], s43, v106
	v_add_co_u32_e32 v108, vcc, s54, v106
	s_nop 0
	v_addc_co_u32_e64 v115, s[8:9], 0, v107, s[8:9]
	v_add_co_u32_e64 v116, s[8:9], s53, v106
	v_addc_co_u32_e32 v109, vcc, 0, v107, vcc
	s_nop 0
	v_addc_co_u32_e64 v117, s[8:9], 0, v107, s[8:9]
	global_load_dwordx4 v[174:177], v[114:115], off
	global_load_dwordx4 v[170:173], v[114:115], off offset:256
	global_load_dwordx4 v[166:169], v[116:117], off
	global_load_dwordx4 v[162:165], v[116:117], off offset:256
	v_add_co_u32_e32 v114, vcc, s59, v106
	global_load_dwordx4 v[182:185], v[108:109], off
	global_load_dwordx4 v[178:181], v[108:109], off offset:256
	v_addc_co_u32_e32 v115, vcc, 0, v107, vcc
	v_add_co_u32_e32 v108, vcc, s60, v106
	global_load_dwordx4 v[158:161], v[114:115], off
	global_load_dwordx4 v[154:157], v[114:115], off offset:256
	v_addc_co_u32_e32 v109, vcc, 0, v107, vcc
	v_add_co_u32_e32 v114, vcc, s61, v106
	global_load_dwordx4 v[150:153], v[108:109], off
	global_load_dwordx4 v[146:149], v[108:109], off offset:256
	v_addc_co_u32_e32 v115, vcc, 0, v107, vcc
	v_add_co_u32_e32 v106, vcc, s62, v106
	global_load_dwordx4 v[134:137], v[114:115], off
	global_load_dwordx4 v[130:133], v[114:115], off offset:256
	v_addc_co_u32_e32 v107, vcc, 0, v107, vcc
	global_load_dwordx4 v[114:117], v[106:107], off
	s_nop 0
	global_load_dwordx4 v[106:109], v[106:107], off offset:256
	v_and_b32_e32 v216, 64, v214
	v_xor_b32_e32 v215, 16, v214
	v_add_u32_e32 v216, 64, v216
	v_xor_b32_e32 v217, 32, v214
	v_cmp_lt_i32_e32 vcc, v215, v216
	s_lshl_b32 s8, s14, 2
	s_ashr_i32 s9, s8, 31
	v_cndmask_b32_e32 v215, v214, v215, vcc
	v_cmp_lt_i32_e32 vcc, v217, v216
	v_lshlrev_b32_e32 v216, 2, v215
	s_waitcnt vmcnt(14)
	v_lshlrev_b32_e32 v228, 16, v218
	v_and_b32_e32 v229, 0xffff0000, v218
	v_lshlrev_b32_e32 v218, 16, v219
	v_and_b32_e32 v219, 0xffff0000, v219
	v_cndmask_b32_e32 v217, v214, v217, vcc
	v_lshlrev_b32_e32 v230, 16, v220
	v_and_b32_e32 v231, 0xffff0000, v220
	v_lshlrev_b32_e32 v220, 16, v221
	v_and_b32_e32 v221, 0xffff0000, v221
	v_pk_add_f32 v[144:145], v[144:145], v[218:219]
	v_pk_add_f32 v[142:143], v[142:143], v[228:229]
	v_lshlrev_b32_e32 v215, 2, v217
	v_pk_add_f32 v[218:219], v[140:141], v[220:221]
	v_pk_add_f32 v[140:141], v[138:139], v[230:231]
	v_mul_f32_e32 v139, v143, v143
	v_mul_f32_e32 v217, v145, v145
	v_mul_f32_e32 v220, v141, v141
	v_fmac_f32_e32 v139, v142, v142
	v_fmac_f32_e32 v217, v144, v144
	v_mul_f32_e32 v221, v219, v219
	v_fmac_f32_e32 v220, v140, v140
	v_add_f32_e32 v139, v139, v217
	v_fmac_f32_e32 v221, v218, v218
	v_add_f32_e32 v139, v220, v139
	v_cvt_pk_bf16_f32 v138, v142, v143
	v_add_f32_e32 v217, v221, v139
	v_cvt_pk_bf16_f32 v139, v144, v145
	v_lshlrev_b32_e32 v142, 16, v222
	v_and_b32_e32 v143, 0xffff0000, v222
	v_lshlrev_b32_e32 v144, 16, v223
	v_and_b32_e32 v145, 0xffff0000, v223
	v_lshlrev_b32_e32 v220, 16, v224
	v_and_b32_e32 v221, 0xffff0000, v224
	v_pk_add_f32 v[128:129], v[128:129], v[144:145]
	v_pk_add_f32 v[126:127], v[126:127], v[142:143]
	v_pk_add_f32 v[144:145], v[122:123], v[220:221]
	v_mul_f32_e32 v122, v127, v127
	v_mul_f32_e32 v123, v129, v129
	v_fmac_f32_e32 v122, v126, v126
	v_fmac_f32_e32 v123, v128, v128
	v_lshlrev_b32_e32 v222, 16, v225
	v_and_b32_e32 v223, 0xffff0000, v225
	v_add_f32_e32 v122, v122, v123
	v_mul_f32_e32 v123, v145, v145
	v_pk_add_f32 v[142:143], v[124:125], v[222:223]
	v_fmac_f32_e32 v123, v144, v144
	v_add_f32_e32 v122, v123, v122
	v_mul_f32_e32 v123, v143, v143
	v_fmac_f32_e32 v123, v142, v142
	v_add_f32_e32 v122, v123, v122
	v_add_f32_e32 v124, v217, v122
	v_mov_b32_e32 v125, v124
	s_nop 1
	v_permlane16_swap_b32_e32 v124, v125
	v_cvt_pk_bf16_f32 v140, v140, v141
	v_cvt_pk_bf16_f32 v141, v218, v219
	v_lshl_add_u64 v[122:123], s[40:41], 0, v[226:227]
	v_cvt_pk_bf16_f32 v126, v126, v127
	s_waitcnt lgkmcnt(0)
	v_add_f32_e32 v124, v124, v125
	v_mov_b32_e32 v125, v124
	s_nop 1
	v_permlane32_swap_b32_e32 v124, v125
	v_cvt_pk_bf16_f32 v127, v128, v129
	v_cvt_pk_bf16_f32 v128, v144, v145
	v_cvt_pk_bf16_f32 v129, v142, v143
	global_store_dwordx4 v[122:123], v[138:141], off
	global_store_dwordx4 v[122:123], v[126:129], off offset:256
	s_and_saveexec_b64 s[30:31], s[4:5]
	s_cbranch_execz .LBB0_1581
	v_lshlrev_b64 v[126:127], 6, v[206:207]
	v_lshl_add_u64 v[126:127], s[10:11], 0, v[126:127]
	v_lshl_add_u64 v[126:127], s[8:9], 2, v[126:127]
	s_lshl_b32 s14, s44, 2
	v_lshl_add_u64 v[126:127], v[126:127], 0, s[14:15]
	s_waitcnt lgkmcnt(0)
	v_add_f32_e32 v124, v124, v125
	global_store_dword v[126:127], v124, off
; __device__ __forceinline__ u32x4 pack8(const f32x4 a, const f32x4 b) { u32x4 w; w.x = cvtpk(a[0], a[1]); w.y = cvtpk(a[2], a[3]); w.z = cvtpk(b[0], b[1]); w.w = cvtpk(b[2], b[3]); return w; }
; __device__ __forceinline__ void unpack8(const u32x4 w, f32x4& a, f32x4& b) { a = (f32x4){bflo(w.x), bfhi(w.x), bflo(w.y), bfhi(w.y)}; b = (f32x4){bflo(w.z), bfhi(w.z), bflo(w.w), bfhi(w.w)}; }
;     __device__ __forceinline__ void operator()(const Acc& acc, const Unit& u, int wr, int wc, int fr, int fq) const {
;     ...
;             for (int m = 0; m < 4; ++m) {
;                 const int row = u.pm * BM + ai * HALF + wr * 64 + m * 16 + fr; float s = 0.f;
; #pragma unroll
;                 for (int bj = 0; bj < 2; ++bj) {
;                     const size_t off = off0 + (size_t)(ai * HALF + m * 16) * D + bj * HALF;
;                     f32x4 b0, b1; unpack8(bw[ai][m][bj], b0, b1);
;                     const f32x4 v0 = b0 + acc[ai][bj][m][0] * scale, v1 = b1 + acc[ai][bj][m][1] * scale;
;                     s += (v0[0] * v0[0] + v0[1] * v0[1]) + (v0[2] * v0[2] + v0[3] * v0[3]) + (v1[0] * v1[0] + v1[1] * v1[1]) + (v1[2] * v1[2] + v1[3] * v1[3]);
;                     if (OUT_F32) { *(f32x4*)(outf + off) = v0; *(f32x4*)(outf + off + 4) = v1; }
;                     if (OUT_BF16) *(u32x4*)(outb + off) = pack8(v0, v1);
;                 }
;                 s += __shfl_xor(s, 16); s += __shfl_xor(s, 32);
;                 if (fq == 0) ssq[(size_t)row * 16 + u.pn * 4 + wc] = s;
;             }
.LBB0_1581:
	s_or_b64 exec, exec, s[30:31]
	s_waitcnt vmcnt(10)
	v_lshlrev_b32_e32 v124, 16, v182
	s_waitcnt lgkmcnt(0)
	v_and_b32_e32 v125, 0xffff0000, v182
	v_lshlrev_b32_e32 v126, 16, v183
	v_and_b32_e32 v127, 0xffff0000, v183
	v_lshlrev_b32_e32 v128, 16, v184
	v_and_b32_e32 v129, 0xffff0000, v184
	v_lshlrev_b32_e32 v138, 16, v185
	v_and_b32_e32 v139, 0xffff0000, v185
	v_pk_add_f32 v[120:121], v[120:121], v[126:127]
	v_pk_add_f32 v[118:119], v[118:119], v[124:125]
	v_pk_add_f32 v[124:125], v[112:113], v[138:139]
	v_pk_add_f32 v[112:113], v[110:111], v[128:129]
	v_mul_f32_e32 v110, v119, v119
	v_mul_f32_e32 v111, v121, v121
	v_fmac_f32_e32 v110, v118, v118
	v_fmac_f32_e32 v111, v120, v120
	v_add_f32_e32 v110, v110, v111
	v_mul_f32_e32 v111, v113, v113
	v_fmac_f32_e32 v111, v112, v112
	v_add_f32_e32 v110, v111, v110
	v_mul_f32_e32 v111, v125, v125
	v_fmac_f32_e32 v111, v124, v124
	v_add_f32_e32 v128, v111, v110
	v_cvt_pk_bf16_f32 v110, v118, v119
	v_cvt_pk_bf16_f32 v111, v120, v121
	v_lshlrev_b32_e32 v118, 16, v178
	v_and_b32_e32 v119, 0xffff0000, v178
	v_lshlrev_b32_e32 v120, 16, v179
	v_and_b32_e32 v121, 0xffff0000, v179
	v_cvt_pk_bf16_f32 v112, v112, v113
	v_cvt_pk_bf16_f32 v113, v124, v125
	v_lshlrev_b32_e32 v124, 16, v180
	v_and_b32_e32 v125, 0xffff0000, v180
	v_pk_add_f32 v[104:105], v[104:105], v[120:121]
	v_pk_add_f32 v[102:103], v[102:103], v[118:119]
	v_pk_add_f32 v[120:121], v[98:99], v[124:125]
	v_mul_f32_e32 v98, v103, v103
	v_mul_f32_e32 v99, v105, v105
	v_fmac_f32_e32 v98, v102, v102
	v_fmac_f32_e32 v99, v104, v104
	v_lshlrev_b32_e32 v126, 16, v181
	v_and_b32_e32 v127, 0xffff0000, v181
	v_add_f32_e32 v98, v98, v99
	v_mul_f32_e32 v99, v121, v121
	v_pk_add_f32 v[118:119], v[100:101], v[126:127]
	v_fmac_f32_e32 v99, v120, v120
	v_add_f32_e32 v98, v99, v98
	v_mul_f32_e32 v99, v119, v119
	v_fmac_f32_e32 v99, v118, v118
	v_add_f32_e32 v98, v99, v98
	v_add_f32_e32 v98, v128, v98
	v_mov_b32_e32 v99, v98
	s_nop 1
	v_permlane16_swap_b32_e32 v98, v99
	v_add_co_u32_e32 v124, vcc, s54, v122
	v_cvt_pk_bf16_f32 v100, v102, v103
	s_nop 0
	v_addc_co_u32_e32 v125, vcc, 0, v123, vcc
	s_waitcnt lgkmcnt(0)
	v_add_f32_e32 v98, v98, v99
	v_mov_b32_e32 v99, v98
	s_nop 1
	v_permlane32_swap_b32_e32 v98, v99
	v_cvt_pk_bf16_f32 v101, v104, v105
	v_cvt_pk_bf16_f32 v102, v120, v121
	v_cvt_pk_bf16_f32 v103, v118, v119
	global_store_dwordx4 v[124:125], v[110:113], off
	global_store_dwordx4 v[124:125], v[100:103], off offset:256
	s_and_saveexec_b64 s[30:31], s[4:5]
	s_cbranch_execz .LBB0_1583
	v_or_b32_e32 v100, 16, v206
	v_ashrrev_i32_e32 v101, 31, v100
	s_waitcnt lgkmcnt(0)
	v_add_f32_e32 v102, v98, v99
	v_lshlrev_b64 v[98:99], 6, v[100:101]
	v_lshl_add_u64 v[98:99], s[10:11], 0, v[98:99]
	v_lshl_add_u64 v[98:99], s[8:9], 2, v[98:99]
	s_lshl_b32 s14, s44, 2
	v_lshl_add_u64 v[98:99], v[98:99], 0, s[14:15]
	global_store_dword v[98:99], v102, off
.LBB0_1583:
	s_or_b64 exec, exec, s[30:31]
	s_waitcnt vmcnt(12)
	v_lshlrev_b32_e32 v98, 16, v174
	s_waitcnt lgkmcnt(0)
	v_and_b32_e32 v99, 0xffff0000, v174
	v_lshlrev_b32_e32 v100, 16, v175
	v_and_b32_e32 v101, 0xffff0000, v175
	v_lshlrev_b32_e32 v102, 16, v176
	v_and_b32_e32 v103, 0xffff0000, v176
	v_lshlrev_b32_e32 v104, 16, v177
	v_and_b32_e32 v105, 0xffff0000, v177
	v_pk_add_f32 v[96:97], v[96:97], v[100:101]
	v_pk_add_f32 v[94:95], v[94:95], v[98:99]
	v_pk_add_f32 v[98:99], v[92:93], v[104:105]
	v_pk_add_f32 v[92:93], v[90:91], v[102:103]
	v_mul_f32_e32 v90, v95, v95
	v_mul_f32_e32 v91, v97, v97
	v_fmac_f32_e32 v90, v94, v94
	v_fmac_f32_e32 v91, v96, v96
	v_add_f32_e32 v90, v90, v91
	v_mul_f32_e32 v91, v93, v93
	v_fmac_f32_e32 v91, v92, v92
	v_add_f32_e32 v90, v91, v90
	v_mul_f32_e32 v91, v99, v99
	v_fmac_f32_e32 v91, v98, v98
	v_add_f32_e32 v102, v91, v90
	v_cvt_pk_bf16_f32 v90, v94, v95
	v_cvt_pk_bf16_f32 v91, v96, v97
	v_lshlrev_b32_e32 v94, 16, v170
	v_and_b32_e32 v95, 0xffff0000, v170
	v_lshlrev_b32_e32 v96, 16, v171
	v_and_b32_e32 v97, 0xffff0000, v171
	v_cvt_pk_bf16_f32 v92, v92, v93
	v_cvt_pk_bf16_f32 v93, v98, v99
	v_lshlrev_b32_e32 v98, 16, v172
	v_and_b32_e32 v99, 0xffff0000, v172
	v_pk_add_f32 v[88:89], v[88:89], v[96:97]
	v_pk_add_f32 v[86:87], v[86:87], v[94:95]
	v_pk_add_f32 v[96:97], v[82:83], v[98:99]
	v_mul_f32_e32 v82, v87, v87
	v_mul_f32_e32 v83, v89, v89
	v_fmac_f32_e32 v82, v86, v86
	v_fmac_f32_e32 v83, v88, v88
	v_lshlrev_b32_e32 v100, 16, v173
	v_and_b32_e32 v101, 0xffff0000, v173
	v_add_f32_e32 v82, v82, v83
	v_mul_f32_e32 v83, v97, v97
	v_pk_add_f32 v[94:95], v[84:85], v[100:101]
	v_fmac_f32_e32 v83, v96, v96
	v_add_f32_e32 v82, v83, v82
	v_mul_f32_e32 v83, v95, v95
	v_fmac_f32_e32 v83, v94, v94
	v_add_f32_e32 v82, v83, v82
	v_add_f32_e32 v82, v102, v82
	v_mov_b32_e32 v83, v82
	s_nop 1
	v_permlane16_swap_b32_e32 v82, v83
	v_add_co_u32_e32 v98, vcc, s43, v122
	v_cvt_pk_bf16_f32 v84, v86, v87
	s_nop 0
	v_addc_co_u32_e32 v99, vcc, 0, v123, vcc
	s_waitcnt lgkmcnt(0)
	v_add_f32_e32 v82, v82, v83
	v_mov_b32_e32 v83, v82
	s_nop 1
	v_permlane32_swap_b32_e32 v82, v83
	v_cvt_pk_bf16_f32 v85, v88, v89
	v_cvt_pk_bf16_f32 v86, v96, v97
	v_cvt_pk_bf16_f32 v87, v94, v95
	global_store_dwordx4 v[98:99], v[90:93], off
	global_store_dwordx4 v[98:99], v[84:87], off offset:256
	s_and_saveexec_b64 s[30:31], s[4:5]
	s_cbranch_execz .LBB0_1585
	v_or_b32_e32 v84, 32, v206
	v_ashrrev_i32_e32 v85, 31, v84
	s_waitcnt lgkmcnt(0)
	v_add_f32_e32 v86, v82, v83
	v_lshlrev_b64 v[82:83], 6, v[84:85]
	v_lshl_add_u64 v[82:83], s[10:11], 0, v[82:83]
	v_lshl_add_u64 v[82:83], s[8:9], 2, v[82:83]
	s_lshl_b32 s14, s44, 2
	v_lshl_add_u64 v[82:83], v[82:83], 0, s[14:15]
	global_store_dword v[82:83], v86, off
; __device__ __forceinline__ u32x4 pack8(const f32x4 a, const f32x4 b) { u32x4 w; w.x = cvtpk(a[0], a[1]); w.y = cvtpk(a[2], a[3]); w.z = cvtpk(b[0], b[1]); w.w = cvtpk(b[2], b[3]); return w; }
; __device__ __forceinline__ void unpack8(const u32x4 w, f32x4& a, f32x4& b) { a = (f32x4){bflo(w.x), bfhi(w.x), bflo(w.y), bfhi(w.y)}; b = (f32x4){bflo(w.z), bfhi(w.z), bflo(w.w), bfhi(w.w)}; }
;     __device__ __forceinline__ void operator()(const Acc& acc, const Unit& u, int wr, int wc, int fr, int fq) const {
;     ...
;             for (int m = 0; m < 4; ++m) {
;                 const int row = u.pm * BM + ai * HALF + wr * 64 + m * 16 + fr; float s = 0.f;
; #pragma unroll
;                 for (int bj = 0; bj < 2; ++bj) {
;                     const size_t off = off0 + (size_t)(ai * HALF + m * 16) * D + bj * HALF;
;                     f32x4 b0, b1; unpack8(bw[ai][m][bj], b0, b1);
;                     const f32x4 v0 = b0 + acc[ai][bj][m][0] * scale, v1 = b1 + acc[ai][bj][m][1] * scale;
;                     s += (v0[0] * v0[0] + v0[1] * v0[1]) + (v0[2] * v0[2] + v0[3] * v0[3]) + (v1[0] * v1[0] + v1[1] * v1[1]) + (v1[2] * v1[2] + v1[3] * v1[3]);
;                     if (OUT_F32) { *(f32x4*)(outf + off) = v0; *(f32x4*)(outf + off + 4) = v1; }
;                     if (OUT_BF16) *(u32x4*)(outb + off) = pack8(v0, v1);
;                 }
;                 s += __shfl_xor(s, 16); s += __shfl_xor(s, 32);
;                 if (fq == 0) ssq[(size_t)row * 16 + u.pn * 4 + wc] = s;
;             }
.LBB0_1585:
	s_or_b64 exec, exec, s[30:31]
	s_waitcnt vmcnt(14)
	v_lshlrev_b32_e32 v82, 16, v166
	s_waitcnt lgkmcnt(0)
	v_and_b32_e32 v83, 0xffff0000, v166
	v_lshlrev_b32_e32 v84, 16, v167
	v_and_b32_e32 v85, 0xffff0000, v167
	v_lshlrev_b32_e32 v86, 16, v168
	v_and_b32_e32 v87, 0xffff0000, v168
	v_lshlrev_b32_e32 v88, 16, v169
	v_and_b32_e32 v89, 0xffff0000, v169
	v_pk_add_f32 v[80:81], v[80:81], v[84:85]
	v_pk_add_f32 v[78:79], v[78:79], v[82:83]
	v_pk_add_f32 v[82:83], v[76:77], v[88:89]
	v_pk_add_f32 v[76:77], v[74:75], v[86:87]
	v_mul_f32_e32 v74, v79, v79
	v_mul_f32_e32 v75, v81, v81
	v_fmac_f32_e32 v74, v78, v78
	v_fmac_f32_e32 v75, v80, v80
	v_add_f32_e32 v74, v74, v75
	v_mul_f32_e32 v75, v77, v77
	v_fmac_f32_e32 v75, v76, v76
	v_add_f32_e32 v74, v75, v74
	v_mul_f32_e32 v75, v83, v83
	v_fmac_f32_e32 v75, v82, v82
	v_add_f32_e32 v86, v75, v74
	v_cvt_pk_bf16_f32 v74, v78, v79
	v_cvt_pk_bf16_f32 v75, v80, v81
	v_lshlrev_b32_e32 v78, 16, v162
	v_and_b32_e32 v79, 0xffff0000, v162
	v_lshlrev_b32_e32 v80, 16, v163
	v_and_b32_e32 v81, 0xffff0000, v163
	v_cvt_pk_bf16_f32 v76, v76, v77
	v_cvt_pk_bf16_f32 v77, v82, v83
	v_lshlrev_b32_e32 v82, 16, v164
	v_and_b32_e32 v83, 0xffff0000, v164
	v_pk_add_f32 v[72:73], v[72:73], v[80:81]
	v_pk_add_f32 v[70:71], v[70:71], v[78:79]
	v_pk_add_f32 v[80:81], v[66:67], v[82:83]
	v_mul_f32_e32 v66, v71, v71
	v_mul_f32_e32 v67, v73, v73
	v_fmac_f32_e32 v66, v70, v70
	v_fmac_f32_e32 v67, v72, v72
	v_lshlrev_b32_e32 v84, 16, v165
	v_and_b32_e32 v85, 0xffff0000, v165
	v_add_f32_e32 v66, v66, v67
	v_mul_f32_e32 v67, v81, v81
	v_pk_add_f32 v[78:79], v[68:69], v[84:85]
	v_fmac_f32_e32 v67, v80, v80
	v_add_f32_e32 v66, v67, v66
	v_mul_f32_e32 v67, v79, v79
	v_fmac_f32_e32 v67, v78, v78
	v_add_f32_e32 v66, v67, v66
	v_add_f32_e32 v66, v86, v66
	v_mov_b32_e32 v67, v66
	s_nop 1
	v_permlane16_swap_b32_e32 v66, v67
	v_add_co_u32_e32 v82, vcc, s53, v122
	v_cvt_pk_bf16_f32 v68, v70, v71
	s_nop 0
	v_addc_co_u32_e32 v83, vcc, 0, v123, vcc
	s_waitcnt lgkmcnt(0)
	v_add_f32_e32 v66, v66, v67
	v_mov_b32_e32 v67, v66
	s_nop 1
	v_permlane32_swap_b32_e32 v66, v67
	v_cvt_pk_bf16_f32 v69, v72, v73
	v_cvt_pk_bf16_f32 v70, v80, v81
	v_cvt_pk_bf16_f32 v71, v78, v79
	global_store_dwordx4 v[82:83], v[74:77], off
	global_store_dwordx4 v[82:83], v[68:71], off offset:256
	s_and_saveexec_b64 s[30:31], s[4:5]
	s_cbranch_execz .LBB0_1587
	v_or_b32_e32 v68, 48, v206
	v_ashrrev_i32_e32 v69, 31, v68
	s_waitcnt lgkmcnt(0)
	v_add_f32_e32 v70, v66, v67
	v_lshlrev_b64 v[66:67], 6, v[68:69]
	v_lshl_add_u64 v[66:67], s[10:11], 0, v[66:67]
	v_lshl_add_u64 v[66:67], s[8:9], 2, v[66:67]
	s_lshl_b32 s14, s44, 2
	v_lshl_add_u64 v[66:67], v[66:67], 0, s[14:15]
	global_store_dword v[66:67], v70, off
.LBB0_1587:
	s_or_b64 exec, exec, s[30:31]
	s_waitcnt vmcnt(14)
	v_lshlrev_b32_e32 v66, 16, v158
	s_waitcnt lgkmcnt(0)
	v_and_b32_e32 v67, 0xffff0000, v158
	v_lshlrev_b32_e32 v68, 16, v159
	v_and_b32_e32 v69, 0xffff0000, v159
	v_lshlrev_b32_e32 v70, 16, v160
	v_and_b32_e32 v71, 0xffff0000, v160
	v_lshlrev_b32_e32 v72, 16, v161
	v_and_b32_e32 v73, 0xffff0000, v161
	v_pk_add_f32 v[64:65], v[64:65], v[68:69]
	v_pk_add_f32 v[62:63], v[62:63], v[66:67]
	v_pk_add_f32 v[66:67], v[60:61], v[72:73]
	v_pk_add_f32 v[60:61], v[58:59], v[70:71]
	v_mul_f32_e32 v58, v63, v63
	v_mul_f32_e32 v59, v65, v65
	v_fmac_f32_e32 v58, v62, v62
	v_fmac_f32_e32 v59, v64, v64
	v_add_f32_e32 v58, v58, v59
	v_mul_f32_e32 v59, v61, v61
	v_fmac_f32_e32 v59, v60, v60
	v_add_f32_e32 v58, v59, v58
	v_mul_f32_e32 v59, v67, v67
	v_fmac_f32_e32 v59, v66, v66
	v_add_f32_e32 v70, v59, v58
	v_cvt_pk_bf16_f32 v58, v62, v63
	v_cvt_pk_bf16_f32 v59, v64, v65
	v_lshlrev_b32_e32 v62, 16, v154
	v_and_b32_e32 v63, 0xffff0000, v154
	v_lshlrev_b32_e32 v64, 16, v155
	v_and_b32_e32 v65, 0xffff0000, v155
	v_cvt_pk_bf16_f32 v60, v60, v61
	v_cvt_pk_bf16_f32 v61, v66, v67
	v_lshlrev_b32_e32 v66, 16, v156
	v_and_b32_e32 v67, 0xffff0000, v156
	v_pk_add_f32 v[56:57], v[56:57], v[64:65]
	v_pk_add_f32 v[54:55], v[54:55], v[62:63]
	v_pk_add_f32 v[64:65], v[50:51], v[66:67]
	v_mul_f32_e32 v50, v55, v55
	v_mul_f32_e32 v51, v57, v57
	v_fmac_f32_e32 v50, v54, v54
	v_fmac_f32_e32 v51, v56, v56
	v_lshlrev_b32_e32 v68, 16, v157
	v_and_b32_e32 v69, 0xffff0000, v157
	v_add_f32_e32 v50, v50, v51
	v_mul_f32_e32 v51, v65, v65
	v_pk_add_f32 v[62:63], v[52:53], v[68:69]
	v_fmac_f32_e32 v51, v64, v64
	v_add_f32_e32 v50, v51, v50
	v_mul_f32_e32 v51, v63, v63
	v_fmac_f32_e32 v51, v62, v62
	v_add_f32_e32 v50, v51, v50
	v_add_f32_e32 v50, v70, v50
	v_mov_b32_e32 v51, v50
	s_nop 1
	v_permlane16_swap_b32_e32 v50, v51
	v_add_co_u32_e32 v66, vcc, s59, v122
	v_cvt_pk_bf16_f32 v52, v54, v55
	s_nop 0
	v_addc_co_u32_e32 v67, vcc, 0, v123, vcc
	s_waitcnt lgkmcnt(0)
	v_add_f32_e32 v50, v50, v51
	v_mov_b32_e32 v51, v50
	s_nop 1
	v_permlane32_swap_b32_e32 v50, v51
	v_cvt_pk_bf16_f32 v53, v56, v57
	v_cvt_pk_bf16_f32 v54, v64, v65
	v_cvt_pk_bf16_f32 v55, v62, v63
	global_store_dwordx4 v[66:67], v[58:61], off
	global_store_dwordx4 v[66:67], v[52:55], off offset:256
	s_and_saveexec_b64 s[30:31], s[4:5]
	s_cbranch_execz .LBB0_1589
	v_add_u32_e32 v52, 0x80, v206
	v_ashrrev_i32_e32 v53, 31, v52
	s_waitcnt lgkmcnt(0)
	v_add_f32_e32 v54, v50, v51
	v_lshlrev_b64 v[50:51], 6, v[52:53]
	v_lshl_add_u64 v[50:51], s[10:11], 0, v[50:51]
	v_lshl_add_u64 v[50:51], s[8:9], 2, v[50:51]
	s_lshl_b32 s14, s44, 2
	v_lshl_add_u64 v[50:51], v[50:51], 0, s[14:15]
	global_store_dword v[50:51], v54, off
; __device__ __forceinline__ u32x4 pack8(const f32x4 a, const f32x4 b) { u32x4 w; w.x = cvtpk(a[0], a[1]); w.y = cvtpk(a[2], a[3]); w.z = cvtpk(b[0], b[1]); w.w = cvtpk(b[2], b[3]); return w; }
; __device__ __forceinline__ void unpack8(const u32x4 w, f32x4& a, f32x4& b) { a = (f32x4){bflo(w.x), bfhi(w.x), bflo(w.y), bfhi(w.y)}; b = (f32x4){bflo(w.z), bfhi(w.z), bflo(w.w), bfhi(w.w)}; }
;     __device__ __forceinline__ void operator()(const Acc& acc, const Unit& u, int wr, int wc, int fr, int fq) const {
;     ...
;             for (int m = 0; m < 4; ++m) {
;                 const int row = u.pm * BM + ai * HALF + wr * 64 + m * 16 + fr; float s = 0.f;
; #pragma unroll
;                 for (int bj = 0; bj < 2; ++bj) {
;                     const size_t off = off0 + (size_t)(ai * HALF + m * 16) * D + bj * HALF;
;                     f32x4 b0, b1; unpack8(bw[ai][m][bj], b0, b1);
;                     const f32x4 v0 = b0 + acc[ai][bj][m][0] * scale, v1 = b1 + acc[ai][bj][m][1] * scale;
;                     s += (v0[0] * v0[0] + v0[1] * v0[1]) + (v0[2] * v0[2] + v0[3] * v0[3]) + (v1[0] * v1[0] + v1[1] * v1[1]) + (v1[2] * v1[2] + v1[3] * v1[3]);
;                     if (OUT_F32) { *(f32x4*)(outf + off) = v0; *(f32x4*)(outf + off + 4) = v1; }
;                     if (OUT_BF16) *(u32x4*)(outb + off) = pack8(v0, v1);
;                 }
;                 s += __shfl_xor(s, 16); s += __shfl_xor(s, 32);
;                 if (fq == 0) ssq[(size_t)row * 16 + u.pn * 4 + wc] = s;
;             }
.LBB0_1589:
	s_or_b64 exec, exec, s[30:31]
	s_waitcnt vmcnt(14)
	v_lshlrev_b32_e32 v50, 16, v150
	s_waitcnt lgkmcnt(0)
	v_and_b32_e32 v51, 0xffff0000, v150
	v_lshlrev_b32_e32 v52, 16, v151
	v_and_b32_e32 v53, 0xffff0000, v151
	v_lshlrev_b32_e32 v54, 16, v152
	v_and_b32_e32 v55, 0xffff0000, v152
	v_lshlrev_b32_e32 v56, 16, v153
	v_and_b32_e32 v57, 0xffff0000, v153
	v_pk_add_f32 v[48:49], v[48:49], v[52:53]
	v_pk_add_f32 v[46:47], v[46:47], v[50:51]
	v_pk_add_f32 v[50:51], v[44:45], v[56:57]
	v_pk_add_f32 v[44:45], v[42:43], v[54:55]
	v_mul_f32_e32 v42, v47, v47
	v_mul_f32_e32 v43, v49, v49
	v_fmac_f32_e32 v42, v46, v46
	v_fmac_f32_e32 v43, v48, v48
	v_add_f32_e32 v42, v42, v43
	v_mul_f32_e32 v43, v45, v45
	v_fmac_f32_e32 v43, v44, v44
	v_add_f32_e32 v42, v43, v42
	v_mul_f32_e32 v43, v51, v51
	v_fmac_f32_e32 v43, v50, v50
	v_add_f32_e32 v54, v43, v42
	v_cvt_pk_bf16_f32 v42, v46, v47
	v_cvt_pk_bf16_f32 v43, v48, v49
	v_lshlrev_b32_e32 v46, 16, v146
	v_and_b32_e32 v47, 0xffff0000, v146
	v_lshlrev_b32_e32 v48, 16, v147
	v_and_b32_e32 v49, 0xffff0000, v147
	v_cvt_pk_bf16_f32 v44, v44, v45
	v_cvt_pk_bf16_f32 v45, v50, v51
	v_lshlrev_b32_e32 v50, 16, v148
	v_and_b32_e32 v51, 0xffff0000, v148
	v_pk_add_f32 v[40:41], v[40:41], v[48:49]
	v_pk_add_f32 v[38:39], v[38:39], v[46:47]
	v_pk_add_f32 v[48:49], v[34:35], v[50:51]
	v_mul_f32_e32 v34, v39, v39
	v_mul_f32_e32 v35, v41, v41
	v_fmac_f32_e32 v34, v38, v38
	v_fmac_f32_e32 v35, v40, v40
	v_lshlrev_b32_e32 v52, 16, v149
	v_and_b32_e32 v53, 0xffff0000, v149
	v_add_f32_e32 v34, v34, v35
	v_mul_f32_e32 v35, v49, v49
	v_pk_add_f32 v[46:47], v[36:37], v[52:53]
	v_fmac_f32_e32 v35, v48, v48
	v_add_f32_e32 v34, v35, v34
	v_mul_f32_e32 v35, v47, v47
	v_fmac_f32_e32 v35, v46, v46
	v_add_f32_e32 v34, v35, v34
	v_add_f32_e32 v34, v54, v34
	v_mov_b32_e32 v35, v34
	s_nop 1
	v_permlane16_swap_b32_e32 v34, v35
	v_add_co_u32_e32 v50, vcc, s60, v122
	v_cvt_pk_bf16_f32 v36, v38, v39
	s_nop 0
	v_addc_co_u32_e32 v51, vcc, 0, v123, vcc
	s_waitcnt lgkmcnt(0)
	v_add_f32_e32 v34, v34, v35
	v_mov_b32_e32 v35, v34
	s_nop 1
	v_permlane32_swap_b32_e32 v34, v35
	v_cvt_pk_bf16_f32 v37, v40, v41
	v_cvt_pk_bf16_f32 v38, v48, v49
	v_cvt_pk_bf16_f32 v39, v46, v47
	global_store_dwordx4 v[50:51], v[42:45], off
	global_store_dwordx4 v[50:51], v[36:39], off offset:256
	s_and_saveexec_b64 s[30:31], s[4:5]
	s_cbranch_execz .LBB0_1591
	v_add_u32_e32 v36, 0x90, v206
	v_ashrrev_i32_e32 v37, 31, v36
	s_waitcnt lgkmcnt(0)
	v_add_f32_e32 v38, v34, v35
	v_lshlrev_b64 v[34:35], 6, v[36:37]
	v_lshl_add_u64 v[34:35], s[10:11], 0, v[34:35]
	v_lshl_add_u64 v[34:35], s[8:9], 2, v[34:35]
	s_lshl_b32 s14, s44, 2
	v_lshl_add_u64 v[34:35], v[34:35], 0, s[14:15]
	global_store_dword v[34:35], v38, off
; __device__ __forceinline__ u32x4 pack8(const f32x4 a, const f32x4 b) { u32x4 w; w.x = cvtpk(a[0], a[1]); w.y = cvtpk(a[2], a[3]); w.z = cvtpk(b[0], b[1]); w.w = cvtpk(b[2], b[3]); return w; }
; __device__ __forceinline__ void unpack8(const u32x4 w, f32x4& a, f32x4& b) { a = (f32x4){bflo(w.x), bfhi(w.x), bflo(w.y), bfhi(w.y)}; b = (f32x4){bflo(w.z), bfhi(w.z), bflo(w.w), bfhi(w.w)}; }
;     __device__ __forceinline__ void operator()(const Acc& acc, const Unit& u, int wr, int wc, int fr, int fq) const {
;     ...
;             for (int m = 0; m < 4; ++m) {
;                 const int row = u.pm * BM + ai * HALF + wr * 64 + m * 16 + fr; float s = 0.f;
; #pragma unroll
;                 for (int bj = 0; bj < 2; ++bj) {
;                     const size_t off = off0 + (size_t)(ai * HALF + m * 16) * D + bj * HALF;
;                     f32x4 b0, b1; unpack8(bw[ai][m][bj], b0, b1);
;                     const f32x4 v0 = b0 + acc[ai][bj][m][0] * scale, v1 = b1 + acc[ai][bj][m][1] * scale;
;                     s += (v0[0] * v0[0] + v0[1] * v0[1]) + (v0[2] * v0[2] + v0[3] * v0[3]) + (v1[0] * v1[0] + v1[1] * v1[1]) + (v1[2] * v1[2] + v1[3] * v1[3]);
;                     if (OUT_F32) { *(f32x4*)(outf + off) = v0; *(f32x4*)(outf + off + 4) = v1; }
;                     if (OUT_BF16) *(u32x4*)(outb + off) = pack8(v0, v1);
;                 }
;                 s += __shfl_xor(s, 16); s += __shfl_xor(s, 32);
;                 if (fq == 0) ssq[(size_t)row * 16 + u.pn * 4 + wc] = s;
;             }
.LBB0_1591:
	s_or_b64 exec, exec, s[30:31]
	s_waitcnt vmcnt(14)
	v_lshlrev_b32_e32 v34, 16, v134
	s_waitcnt lgkmcnt(0)
	v_and_b32_e32 v35, 0xffff0000, v134
	v_lshlrev_b32_e32 v36, 16, v135
	v_and_b32_e32 v37, 0xffff0000, v135
	v_lshlrev_b32_e32 v38, 16, v136
	v_and_b32_e32 v39, 0xffff0000, v136
	v_lshlrev_b32_e32 v40, 16, v137
	v_and_b32_e32 v41, 0xffff0000, v137
	v_pk_add_f32 v[32:33], v[32:33], v[36:37]
	v_pk_add_f32 v[30:31], v[30:31], v[34:35]
	v_pk_add_f32 v[34:35], v[28:29], v[40:41]
	v_pk_add_f32 v[28:29], v[26:27], v[38:39]
	v_mul_f32_e32 v26, v31, v31
	v_mul_f32_e32 v27, v33, v33
	v_fmac_f32_e32 v26, v30, v30
	v_fmac_f32_e32 v27, v32, v32
	v_add_f32_e32 v26, v26, v27
	v_mul_f32_e32 v27, v29, v29
	v_fmac_f32_e32 v27, v28, v28
	v_add_f32_e32 v26, v27, v26
	v_mul_f32_e32 v27, v35, v35
	v_fmac_f32_e32 v27, v34, v34
	v_add_f32_e32 v38, v27, v26
	v_cvt_pk_bf16_f32 v26, v30, v31
	v_cvt_pk_bf16_f32 v27, v32, v33
	v_lshlrev_b32_e32 v30, 16, v130
	v_and_b32_e32 v31, 0xffff0000, v130
	v_lshlrev_b32_e32 v32, 16, v131
	v_and_b32_e32 v33, 0xffff0000, v131
	v_cvt_pk_bf16_f32 v28, v28, v29
	v_cvt_pk_bf16_f32 v29, v34, v35
	v_lshlrev_b32_e32 v34, 16, v132
	v_and_b32_e32 v35, 0xffff0000, v132
	v_pk_add_f32 v[24:25], v[24:25], v[32:33]
	v_pk_add_f32 v[22:23], v[22:23], v[30:31]
	v_pk_add_f32 v[32:33], v[18:19], v[34:35]
	v_mul_f32_e32 v18, v23, v23
	v_mul_f32_e32 v19, v25, v25
	v_fmac_f32_e32 v18, v22, v22
	v_fmac_f32_e32 v19, v24, v24
	v_lshlrev_b32_e32 v36, 16, v133
	v_and_b32_e32 v37, 0xffff0000, v133
	v_add_f32_e32 v18, v18, v19
	v_mul_f32_e32 v19, v33, v33
	v_pk_add_f32 v[30:31], v[20:21], v[36:37]
	v_fmac_f32_e32 v19, v32, v32
	v_add_f32_e32 v18, v19, v18
	v_mul_f32_e32 v19, v31, v31
	v_fmac_f32_e32 v19, v30, v30
	v_add_f32_e32 v18, v19, v18
	v_add_f32_e32 v18, v38, v18
	v_mov_b32_e32 v19, v18
	s_nop 1
	v_permlane16_swap_b32_e32 v18, v19
	v_add_co_u32_e32 v34, vcc, s61, v122
	v_cvt_pk_bf16_f32 v20, v22, v23
	s_nop 0
	v_addc_co_u32_e32 v35, vcc, 0, v123, vcc
	s_waitcnt lgkmcnt(0)
	v_add_f32_e32 v18, v18, v19
	v_mov_b32_e32 v19, v18
	s_nop 1
	v_permlane32_swap_b32_e32 v18, v19
	v_cvt_pk_bf16_f32 v21, v24, v25
	v_cvt_pk_bf16_f32 v22, v32, v33
	v_cvt_pk_bf16_f32 v23, v30, v31
	global_store_dwordx4 v[34:35], v[26:29], off
	global_store_dwordx4 v[34:35], v[20:23], off offset:256
	s_and_saveexec_b64 s[30:31], s[4:5]
	s_cbranch_execz .LBB0_1593
	v_add_u32_e32 v20, 0xa0, v206
	v_ashrrev_i32_e32 v21, 31, v20
	s_waitcnt lgkmcnt(0)
	v_add_f32_e32 v22, v18, v19
	v_lshlrev_b64 v[18:19], 6, v[20:21]
	v_lshl_add_u64 v[18:19], s[10:11], 0, v[18:19]
	v_lshl_add_u64 v[18:19], s[8:9], 2, v[18:19]
	s_lshl_b32 s14, s44, 2
	v_lshl_add_u64 v[18:19], v[18:19], 0, s[14:15]
	global_store_dword v[18:19], v22, off
.LBB0_1593:
	s_or_b64 exec, exec, s[30:31]
	s_waitcnt vmcnt(14)
	v_lshlrev_b32_e32 v18, 16, v114
	s_waitcnt lgkmcnt(0)
	v_and_b32_e32 v19, 0xffff0000, v114
	v_lshlrev_b32_e32 v20, 16, v115
	v_and_b32_e32 v21, 0xffff0000, v115
	v_lshlrev_b32_e32 v22, 16, v116
	v_and_b32_e32 v23, 0xffff0000, v116
	v_lshlrev_b32_e32 v24, 16, v117
	v_and_b32_e32 v25, 0xffff0000, v117
	v_pk_add_f32 v[16:17], v[16:17], v[20:21]
	v_pk_add_f32 v[14:15], v[14:15], v[18:19]
	v_pk_add_f32 v[18:19], v[12:13], v[24:25]
	v_pk_add_f32 v[12:13], v[10:11], v[22:23]
	v_mul_f32_e32 v10, v15, v15
	v_mul_f32_e32 v11, v17, v17
	v_fmac_f32_e32 v10, v14, v14
	v_fmac_f32_e32 v11, v16, v16
	v_add_f32_e32 v10, v10, v11
	v_mul_f32_e32 v11, v13, v13
	v_fmac_f32_e32 v11, v12, v12
	v_add_f32_e32 v10, v11, v10
	v_mul_f32_e32 v11, v19, v19
	v_fmac_f32_e32 v11, v18, v18
	v_add_f32_e32 v22, v11, v10
	v_cvt_pk_bf16_f32 v10, v14, v15
	v_cvt_pk_bf16_f32 v11, v16, v17
	v_lshlrev_b32_e32 v14, 16, v106
	v_and_b32_e32 v15, 0xffff0000, v106
	v_lshlrev_b32_e32 v16, 16, v107
	v_and_b32_e32 v17, 0xffff0000, v107
	v_cvt_pk_bf16_f32 v12, v12, v13
	v_cvt_pk_bf16_f32 v13, v18, v19
	v_lshlrev_b32_e32 v18, 16, v108
	v_and_b32_e32 v19, 0xffff0000, v108
	v_pk_add_f32 v[8:9], v[8:9], v[16:17]
	v_pk_add_f32 v[6:7], v[6:7], v[14:15]
	v_pk_add_f32 v[16:17], v[2:3], v[18:19]
	v_mul_f32_e32 v2, v7, v7
	v_mul_f32_e32 v3, v9, v9
	v_fmac_f32_e32 v2, v6, v6
	v_fmac_f32_e32 v3, v8, v8
	v_lshlrev_b32_e32 v20, 16, v109
	v_and_b32_e32 v21, 0xffff0000, v109
	v_add_f32_e32 v2, v2, v3
	v_mul_f32_e32 v3, v17, v17
	v_pk_add_f32 v[14:15], v[4:5], v[20:21]
	v_fmac_f32_e32 v3, v16, v16
	v_add_f32_e32 v2, v3, v2
	v_mul_f32_e32 v3, v15, v15
	v_fmac_f32_e32 v3, v14, v14
	v_add_f32_e32 v2, v3, v2
	v_add_f32_e32 v2, v22, v2
	v_mov_b32_e32 v3, v2
	s_nop 1
	v_permlane16_swap_b32_e32 v2, v3
	v_add_co_u32_e32 v18, vcc, s62, v122
	v_cvt_pk_bf16_f32 v4, v6, v7
	s_nop 0
	v_addc_co_u32_e32 v19, vcc, 0, v123, vcc
	s_waitcnt lgkmcnt(0)
	v_add_f32_e32 v2, v2, v3
	v_mov_b32_e32 v3, v2
	s_nop 1
	v_permlane32_swap_b32_e32 v2, v3
	v_cvt_pk_bf16_f32 v5, v8, v9
	v_cvt_pk_bf16_f32 v6, v16, v17
	v_cvt_pk_bf16_f32 v7, v14, v15
	global_store_dwordx4 v[18:19], v[10:13], off
	global_store_dwordx4 v[18:19], v[4:7], off offset:256
	s_and_saveexec_b64 s[30:31], s[4:5]
	s_cbranch_execz .LBB0_1595
	v_add_u32_e32 v4, 0xb0, v206
	v_ashrrev_i32_e32 v5, 31, v4
	s_waitcnt lgkmcnt(0)
	v_add_f32_e32 v6, v2, v3
	v_lshlrev_b64 v[2:3], 6, v[4:5]
	v_lshl_add_u64 v[2:3], s[10:11], 0, v[2:3]
	v_lshl_add_u64 v[2:3], s[8:9], 2, v[2:3]
	s_lshl_b32 s14, s44, 2
	v_lshl_add_u64 v[2:3], v[2:3], 0, s[14:15]
	global_store_dword v[2:3], v6, off
